# ph_prep: query path K loop double-buffered (fragments requested one K-step ahead into path-private registers); key/value path now requests every fragment one K-step ahead (aliasing sum-of-squares temp
# speedup vs baseline: 1.0071x; 1.0005x over previous
; __device__ __forceinline__ float bf2f(bf16_t v) { return __uint_as_float(((unsigned)v) << 16); }
; #define LAS __attribute__((address_space(3)))
; __device__ __forceinline__ void ph_prep(bf16_t* Z, const bf16_t* WUQ, const bf16_t* WUKV, const bf16_t* D64, const float* qkq, const float* qkk,
;                                         bf16_t* Q, bf16_t* Kb, bf16_t* Vb, bf16_t* F1lat, bf16_t* F1ctx, unsigned char* lds_) { PH_IDS;
;     ...
;             for (int pass = 0; pass < 2; ++pass) {
;                 f32x4 acc[4][3];
; #pragma unroll
;                 for (int tt = 0; tt < 3; ++tt)
; #pragma unroll
;                     for (int nt = 0; nt < 4; ++nt) acc[nt][tt] = (f32x4){0.f, 0.f, 0.f, 0.f};
; #pragma unroll
;                 for (int ks = 0; ks < 4; ++ks) {
;                     bf16x8 bq[3], aw[4];
; #pragma unroll
;                     for (int tt = 0; tt < 3; ++tt) { bq[tt] = *(const LAS bf16x8*)(sm + O_KV + rl[tt] * P_KV + (32 * ks + 8 * kq) * 2);
;                         if (pass == 0) {
; #pragma unroll
;                             for (int e = 0; e < 8; ++e) { const float f = bf2f((bf16_t)bq[tt][e]); ssq[tt] += f * f; } } }
; #pragma unroll
;                     for (int nt = 0; nt < 4; ++nt) aw[nt] = *(const bf16x8*)(WUKV + (size_t)(h * 128 + pass * 64 + 16 * nt + c16) * 128 + 32 * ks + 8 * kq);
; #pragma unroll
;                     for (int nt = 0; nt < 4; ++nt)
; #pragma unroll
;                         for (int tt = 0; tt < 3; ++tt) acc[nt][tt] = __builtin_amdgcn_mfma_f32_16x16x32_bf16(aw[nt], bq[tt], acc[nt][tt], 0, 0, 0);
;                 }
.LBB0_501:
	v_or_b32_e32 v38, s61, v173
	v_ashrrev_i32_e32 v39, 31, v38
	v_lshlrev_b64 v[22:23], 8, v[38:39]
	v_lshl_add_u64 v[150:151], v[102:103], 0, v[22:23]
	v_or_b32_e32 v22, 16, v38
	v_or_b32_e32 v34, 32, v38
	v_or_b32_e32 v46, 48, v38
	v_ashrrev_i32_e32 v23, 31, v22
	v_ashrrev_i32_e32 v35, 31, v34
	v_ashrrev_i32_e32 v47, 31, v46
	v_lshlrev_b64 v[22:23], 8, v[22:23]
	v_lshlrev_b64 v[34:35], 8, v[34:35]
	v_lshlrev_b64 v[46:47], 8, v[46:47]
	v_lshl_add_u64 v[152:153], v[102:103], 0, v[22:23]
	v_lshl_add_u64 v[154:155], v[102:103], 0, v[34:35]
	v_lshl_add_u64 v[156:157], v[102:103], 0, v[46:47]
	global_load_dwordx4 v[30:33], v[150:151], off
	global_load_dwordx4 v[42:45], v[152:153], off
	global_load_dwordx4 v[54:57], v[154:155], off
	global_load_dwordx4 v[70:73], v[156:157], off
	global_load_dwordx4 v[78:81], v[150:151], off offset:64
	global_load_dwordx4 v[82:85], v[152:153], off offset:64
	global_load_dwordx4 v[110:113], v[154:155], off offset:64
	global_load_dwordx4 v[134:137], v[156:157], off offset:64
	ds_read_b128 v[66:69], v86 offset:64
	s_and_b64 vcc, exec, s[18:19]
	s_waitcnt vmcnt(7) lgkmcnt(3)
	v_mfma_f32_16x16x32_bf16 v[22:25], v[30:33], v[18:21], 0
	s_waitcnt lgkmcnt(2)
	v_mfma_f32_16x16x32_bf16 v[26:29], v[30:33], v[58:61], 0
	s_waitcnt lgkmcnt(1)
	v_mfma_f32_16x16x32_bf16 v[30:33], v[30:33], v[62:65], 0
	s_waitcnt vmcnt(6)
	v_mfma_f32_16x16x32_bf16 v[34:37], v[42:45], v[18:21], 0
	v_mfma_f32_16x16x32_bf16 v[38:41], v[42:45], v[58:61], 0
	v_mfma_f32_16x16x32_bf16 v[42:45], v[42:45], v[62:65], 0
	s_waitcnt vmcnt(5)
	v_mfma_f32_16x16x32_bf16 v[46:49], v[54:57], v[18:21], 0
	v_mfma_f32_16x16x32_bf16 v[50:53], v[54:57], v[58:61], 0
	v_mfma_f32_16x16x32_bf16 v[54:57], v[54:57], v[62:65], 0
	s_waitcnt vmcnt(4)
	v_mfma_f32_16x16x32_bf16 v[18:21], v[70:73], v[18:21], 0
	v_mfma_f32_16x16x32_bf16 v[58:61], v[70:73], v[58:61], 0
	v_mfma_f32_16x16x32_bf16 v[62:65], v[70:73], v[62:65], 0
	s_cbranch_vccnz .LBB0_542
	s_waitcnt lgkmcnt(0)
	v_and_b32_e32 v71, 0xffff0000, v66
	v_lshlrev_b32_e32 v70, 16, v66
	v_pk_mul_f32 v[70:71], v[70:71], v[70:71]
	s_nop 0
	v_add_f32_e32 v70, v253, v70
	v_add_f32_e32 v72, v71, v70
	v_and_b32_e32 v71, 0xffff0000, v67
	v_lshlrev_b32_e32 v70, 16, v67
	v_pk_mul_f32 v[70:71], v[70:71], v[70:71]
	s_nop 0
	v_add_f32_e32 v70, v70, v72
	v_add_f32_e32 v72, v71, v70
	v_and_b32_e32 v71, 0xffff0000, v68
	v_lshlrev_b32_e32 v70, 16, v68
	v_pk_mul_f32 v[70:71], v[70:71], v[70:71]
	s_nop 0
	v_add_f32_e32 v70, v70, v72
	v_add_f32_e32 v72, v71, v70
	v_and_b32_e32 v71, 0xffff0000, v69
	v_lshlrev_b32_e32 v70, 16, v69
	v_pk_mul_f32 v[70:71], v[70:71], v[70:71]
	s_nop 0
	v_add_f32_e32 v70, v70, v72
	v_add_f32_e32 v253, v71, v70
	ds_read_b128 v[70:73], v94 offset:64
	s_and_b64 vcc, exec, s[18:19]
	s_cbranch_vccz .LBB0_543

; __device__ __forceinline__ float bf2f(bf16_t v) { return __uint_as_float(((unsigned)v) << 16); }
; #define LAS __attribute__((address_space(3)))
; __device__ __forceinline__ void ph_prep(bf16_t* Z, const bf16_t* WUQ, const bf16_t* WUKV, const bf16_t* D64, const float* qkq, const float* qkk,
;                                         bf16_t* Q, bf16_t* Kb, bf16_t* Vb, bf16_t* F1lat, bf16_t* F1ctx, unsigned char* lds_) { PH_IDS;
;     ...
;                 for (int ks = 0; ks < 4; ++ks) {
;                     bf16x8 bq[3], aw[4];
; #pragma unroll
;                     for (int tt = 0; tt < 3; ++tt) { bq[tt] = *(const LAS bf16x8*)(sm + O_KV + rl[tt] * P_KV + (32 * ks + 8 * kq) * 2);
;                         if (pass == 0) {
; #pragma unroll
;                             for (int e = 0; e < 8; ++e) { const float f = bf2f((bf16_t)bq[tt][e]); ssq[tt] += f * f; } } }
; #pragma unroll
;                     for (int nt = 0; nt < 4; ++nt) aw[nt] = *(const bf16x8*)(WUKV + (size_t)(h * 128 + pass * 64 + 16 * nt + c16) * 128 + 32 * ks + 8 * kq);
; #pragma unroll
;                     for (int nt = 0; nt < 4; ++nt)
; #pragma unroll
;                         for (int tt = 0; tt < 3; ++tt) acc[nt][tt] = __builtin_amdgcn_mfma_f32_16x16x32_bf16(aw[nt], bq[tt], acc[nt][tt], 0, 0, 0);
;                 }
.LBB0_504:
	s_waitcnt lgkmcnt(0)
	v_and_b32_e32 v125, 0xffff0000, v74
	v_lshlrev_b32_e32 v124, 16, v74
	v_pk_mul_f32 v[124:125], v[124:125], v[124:125]
	s_nop 0
	v_add_f32_e32 v124, v251, v124
	v_add_f32_e32 v98, v125, v124
	v_and_b32_e32 v125, 0xffff0000, v75
	v_lshlrev_b32_e32 v124, 16, v75
	v_pk_mul_f32 v[124:125], v[124:125], v[124:125]
	s_nop 0
	v_add_f32_e32 v124, v124, v98
	v_add_f32_e32 v98, v125, v124
	v_and_b32_e32 v125, 0xffff0000, v76
	v_lshlrev_b32_e32 v124, 16, v76
	v_pk_mul_f32 v[124:125], v[124:125], v[124:125]
	s_nop 0
	v_add_f32_e32 v124, v124, v98
	v_add_f32_e32 v98, v125, v124
	v_and_b32_e32 v125, 0xffff0000, v77
	v_lshlrev_b32_e32 v124, 16, v77
	v_pk_mul_f32 v[124:125], v[124:125], v[124:125]
	s_nop 0
	v_add_f32_e32 v124, v124, v98
	v_add_f32_e32 v251, v125, v124
.LBB0_505:
	s_and_b64 vcc, exec, s[18:19]
	s_waitcnt vmcnt(3) lgkmcnt(2)
	v_mfma_f32_16x16x32_bf16 v[22:25], v[78:81], v[66:69], v[22:25]
	s_waitcnt lgkmcnt(1)
	v_mfma_f32_16x16x32_bf16 v[26:29], v[78:81], v[70:73], v[26:29]
	s_waitcnt lgkmcnt(0)
	v_mfma_f32_16x16x32_bf16 v[30:33], v[78:81], v[74:77], v[30:33]
	s_waitcnt vmcnt(2)
	v_mfma_f32_16x16x32_bf16 v[34:37], v[82:85], v[66:69], v[34:37]
	v_mfma_f32_16x16x32_bf16 v[38:41], v[82:85], v[70:73], v[38:41]
	v_mfma_f32_16x16x32_bf16 v[42:45], v[82:85], v[74:77], v[42:45]
	s_waitcnt vmcnt(1)
	v_mfma_f32_16x16x32_bf16 v[46:49], v[110:113], v[66:69], v[46:49]
	v_mfma_f32_16x16x32_bf16 v[50:53], v[110:113], v[70:73], v[50:53]
	v_mfma_f32_16x16x32_bf16 v[54:57], v[110:113], v[74:77], v[54:57]
	ds_read_b128 v[78:81], v86 offset:128
	s_waitcnt vmcnt(0)
	v_mfma_f32_16x16x32_bf16 v[18:21], v[134:137], v[66:69], v[18:21]
	v_mfma_f32_16x16x32_bf16 v[58:61], v[134:137], v[70:73], v[58:61]
	v_mfma_f32_16x16x32_bf16 v[62:65], v[134:137], v[74:77], v[62:65]
	global_load_dwordx4 v[66:69], v[150:151], off offset:128
	global_load_dwordx4 v[70:73], v[152:153], off offset:128
	global_load_dwordx4 v[74:77], v[154:155], off offset:128
	global_load_dwordx4 v[110:113], v[156:157], off offset:128
	global_load_dwordx4 v[134:137], v[154:155], off offset:192
	s_cbranch_vccnz .LBB0_544
	s_waitcnt lgkmcnt(0)
	v_and_b32_e32 v125, 0xffff0000, v78
	v_lshlrev_b32_e32 v124, 16, v78
	v_pk_mul_f32 v[124:125], v[124:125], v[124:125]
	s_nop 0
	v_add_f32_e32 v124, v253, v124
	v_add_f32_e32 v98, v125, v124
	v_and_b32_e32 v125, 0xffff0000, v79
	v_lshlrev_b32_e32 v124, 16, v79
	v_pk_mul_f32 v[124:125], v[124:125], v[124:125]
	s_nop 0
	v_add_f32_e32 v124, v124, v98
	v_add_f32_e32 v98, v125, v124
	v_and_b32_e32 v125, 0xffff0000, v80
	v_lshlrev_b32_e32 v124, 16, v80
	v_pk_mul_f32 v[124:125], v[124:125], v[124:125]
	s_nop 0
	v_add_f32_e32 v124, v124, v98
	v_add_f32_e32 v98, v125, v124
	v_and_b32_e32 v125, 0xffff0000, v81
	v_lshlrev_b32_e32 v124, 16, v81
	v_pk_mul_f32 v[124:125], v[124:125], v[124:125]
	s_nop 0
	v_add_f32_e32 v124, v124, v98
	v_add_f32_e32 v253, v125, v124
	ds_read_b128 v[82:85], v94 offset:128
	s_and_b64 vcc, exec, s[18:19]
	s_cbranch_vccz .LBB0_545

; __device__ __forceinline__ float bf2f(bf16_t v) { return __uint_as_float(((unsigned)v) << 16); }
; #define LAS __attribute__((address_space(3)))
; __device__ __forceinline__ void ph_prep(bf16_t* Z, const bf16_t* WUQ, const bf16_t* WUKV, const bf16_t* D64, const float* qkq, const float* qkk,
;                                         bf16_t* Q, bf16_t* Kb, bf16_t* Vb, bf16_t* F1lat, bf16_t* F1ctx, unsigned char* lds_) { PH_IDS;
;     ...
;                 for (int ks = 0; ks < 4; ++ks) {
;                     bf16x8 bq[3], aw[4];
; #pragma unroll
;                     for (int tt = 0; tt < 3; ++tt) { bq[tt] = *(const LAS bf16x8*)(sm + O_KV + rl[tt] * P_KV + (32 * ks + 8 * kq) * 2);
;                         if (pass == 0) {
; #pragma unroll
;                             for (int e = 0; e < 8; ++e) { const float f = bf2f((bf16_t)bq[tt][e]); ssq[tt] += f * f; } } }
; #pragma unroll
;                     for (int nt = 0; nt < 4; ++nt) aw[nt] = *(const bf16x8*)(WUKV + (size_t)(h * 128 + pass * 64 + 16 * nt + c16) * 128 + 32 * ks + 8 * kq);
; #pragma unroll
;                     for (int nt = 0; nt < 4; ++nt)
; #pragma unroll
;                         for (int tt = 0; tt < 3; ++tt) acc[nt][tt] = __builtin_amdgcn_mfma_f32_16x16x32_bf16(aw[nt], bq[tt], acc[nt][tt], 0, 0, 0);
;                 }
.LBB0_508:
	s_waitcnt lgkmcnt(0)
	v_and_b32_e32 v125, 0xffff0000, v90
	v_lshlrev_b32_e32 v124, 16, v90
	v_pk_mul_f32 v[124:125], v[124:125], v[124:125]
	s_nop 0
	v_add_f32_e32 v124, v251, v124
	v_add_f32_e32 v98, v125, v124
	v_and_b32_e32 v125, 0xffff0000, v91
	v_lshlrev_b32_e32 v124, 16, v91
	v_pk_mul_f32 v[124:125], v[124:125], v[124:125]
	s_nop 0
	v_add_f32_e32 v124, v124, v98
	v_add_f32_e32 v98, v125, v124
	v_and_b32_e32 v125, 0xffff0000, v92
	v_lshlrev_b32_e32 v124, 16, v92
	v_pk_mul_f32 v[124:125], v[124:125], v[124:125]
	s_nop 0
	v_add_f32_e32 v124, v124, v98
	v_add_f32_e32 v98, v125, v124
	v_and_b32_e32 v125, 0xffff0000, v93
	v_lshlrev_b32_e32 v124, 16, v93
	v_pk_mul_f32 v[124:125], v[124:125], v[124:125]
	s_nop 0
	v_add_f32_e32 v124, v124, v98
	v_add_f32_e32 v251, v125, v124
.LBB0_509:
	ds_read_b128 v[86:89], v86 offset:192
	s_and_b64 vcc, exec, s[18:19]
	s_waitcnt vmcnt(4) lgkmcnt(3)
	v_mfma_f32_16x16x32_bf16 v[22:25], v[66:69], v[78:81], v[22:25]
	s_waitcnt lgkmcnt(2)
	v_mfma_f32_16x16x32_bf16 v[26:29], v[66:69], v[82:85], v[26:29]
	s_waitcnt lgkmcnt(1)
	v_mfma_f32_16x16x32_bf16 v[30:33], v[66:69], v[90:93], v[30:33]
	s_waitcnt vmcnt(3)
	v_mfma_f32_16x16x32_bf16 v[66:69], v[70:73], v[90:93], v[42:45]
	s_nop 2
	v_mfma_f32_16x16x32_bf16 v[34:37], v[70:73], v[78:81], v[34:37]
	v_mfma_f32_16x16x32_bf16 v[38:41], v[70:73], v[82:85], v[38:41]
	s_waitcnt vmcnt(2)
	v_mfma_f32_16x16x32_bf16 v[70:73], v[74:77], v[78:81], v[46:49]
	v_mfma_f32_16x16x32_bf16 v[50:53], v[74:77], v[82:85], v[50:53]
	v_mfma_f32_16x16x32_bf16 v[74:77], v[74:77], v[90:93], v[54:57]
	s_waitcnt vmcnt(1)
	v_mfma_f32_16x16x32_bf16 v[18:21], v[110:113], v[78:81], v[18:21]
	v_mfma_f32_16x16x32_bf16 v[78:81], v[110:113], v[82:85], v[58:61]
	v_mfma_f32_16x16x32_bf16 v[82:85], v[110:113], v[90:93], v[62:65]
	global_load_dwordx4 v[42:45], v[150:151], off offset:192
	global_load_dwordx4 v[54:57], v[152:153], off offset:192
	global_load_dwordx4 v[110:113], v[156:157], off offset:192
	s_cbranch_vccnz .LBB0_546
	s_waitcnt lgkmcnt(0)
	v_and_b32_e32 v125, 0xffff0000, v86
	v_lshlrev_b32_e32 v124, 16, v86
	v_pk_mul_f32 v[124:125], v[124:125], v[124:125]
	s_nop 0
	v_add_f32_e32 v124, v253, v124
	v_add_f32_e32 v98, v125, v124
	v_and_b32_e32 v125, 0xffff0000, v87
	v_lshlrev_b32_e32 v124, 16, v87
	v_pk_mul_f32 v[124:125], v[124:125], v[124:125]
	s_nop 0
	v_add_f32_e32 v124, v124, v98
	v_add_f32_e32 v98, v125, v124
	v_and_b32_e32 v125, 0xffff0000, v88
	v_lshlrev_b32_e32 v124, 16, v88
	v_pk_mul_f32 v[124:125], v[124:125], v[124:125]
	s_nop 0
	v_add_f32_e32 v124, v124, v98
	v_add_f32_e32 v98, v125, v124
	v_and_b32_e32 v125, 0xffff0000, v89
	v_lshlrev_b32_e32 v124, 16, v89
	v_pk_mul_f32 v[124:125], v[124:125], v[124:125]
	s_nop 0
	v_add_f32_e32 v124, v124, v98
	v_add_f32_e32 v253, v125, v124
	ds_read_b128 v[90:93], v94 offset:192
	s_and_b64 vcc, exec, s[18:19]
	s_cbranch_vccz .LBB0_547

; __device__ __forceinline__ float bf2f(bf16_t v) { return __uint_as_float(((unsigned)v) << 16); }
; #define LAS __attribute__((address_space(3)))
; __device__ __forceinline__ unsigned pk2(float lo, float hi) { unsigned r; asm volatile("v_cvt_pk_bf16_f32 %0, %1, %2" : "=v"(r) : "v"(lo), "v"(hi)); return r; }
; __device__ __forceinline__ void ph_prep(bf16_t* Z, const bf16_t* WUQ, const bf16_t* WUKV, const bf16_t* D64, const float* qkq, const float* qkk,
;                                         bf16_t* Q, bf16_t* Kb, bf16_t* Vb, bf16_t* F1lat, bf16_t* F1ctx, unsigned char* lds_) { PH_IDS;
;     ...
;                 for (int ks = 0; ks < 4; ++ks) {
;                     bf16x8 bq[3], aw[4];
; #pragma unroll
;                     for (int tt = 0; tt < 3; ++tt) { bq[tt] = *(const LAS bf16x8*)(sm + O_KV + rl[tt] * P_KV + (32 * ks + 8 * kq) * 2);
;                         if (pass == 0) {
; #pragma unroll
;                             for (int e = 0; e < 8; ++e) { const float f = bf2f((bf16_t)bq[tt][e]); ssq[tt] += f * f; } } }
; #pragma unroll
;                     for (int nt = 0; nt < 4; ++nt) aw[nt] = *(const bf16x8*)(WUKV + (size_t)(h * 128 + pass * 64 + 16 * nt + c16) * 128 + 32 * ks + 8 * kq);
; #pragma unroll
;                     for (int nt = 0; nt < 4; ++nt)
; #pragma unroll
;                         for (int tt = 0; tt < 3; ++tt) acc[nt][tt] = __builtin_amdgcn_mfma_f32_16x16x32_bf16(aw[nt], bq[tt], acc[nt][tt], 0, 0, 0);
;                 }
;     ...
;                         bf16_t* vo = Vb + ((size_t)(b * 4 + h) * 2304 + ki) * 64 + 4 * kq;
; #pragma unroll
;                         for (int nt = 0; nt < 4; ++nt) { fa::u32x2 o; o.x = fa::pk2(acc[nt][tt][0] * rstd[tt], acc[nt][tt][1] * rstd[tt]); o.y = fa::pk2(acc[nt][tt][2] * rstd[tt], acc[nt][tt][3] * rstd[tt]);
;                             if (valid[tt]) *(fa::u32x2*)(vo + 16 * nt) = o; }
.LBB0_512:
	s_waitcnt lgkmcnt(0)
	v_and_b32_e32 v125, 0xffff0000, v94
	v_lshlrev_b32_e32 v124, 16, v94
	v_pk_mul_f32 v[124:125], v[124:125], v[124:125]
	s_nop 0
	v_add_f32_e32 v124, v251, v124
	v_add_f32_e32 v98, v125, v124
	v_and_b32_e32 v125, 0xffff0000, v95
	v_lshlrev_b32_e32 v124, 16, v95
	v_pk_mul_f32 v[124:125], v[124:125], v[124:125]
	s_nop 0
	v_add_f32_e32 v124, v124, v98
	v_add_f32_e32 v98, v125, v124
	v_and_b32_e32 v125, 0xffff0000, v96
	v_lshlrev_b32_e32 v124, 16, v96
	v_pk_mul_f32 v[124:125], v[124:125], v[124:125]
	s_nop 0
	v_add_f32_e32 v124, v124, v98
	v_add_f32_e32 v98, v125, v124
	v_and_b32_e32 v125, 0xffff0000, v97
	v_lshlrev_b32_e32 v124, 16, v97
	v_pk_mul_f32 v[124:125], v[124:125], v[124:125]
	s_nop 0
	v_add_f32_e32 v124, v124, v98
	v_add_f32_e32 v251, v125, v124
.LBB0_513:
	s_mov_b64 s[18:19], -1
	s_and_b64 vcc, exec, s[34:35]
	s_waitcnt vmcnt(2) lgkmcnt(2)
	v_mfma_f32_16x16x32_bf16 v[62:65], v[42:45], v[86:89], v[22:25]
	s_nop 2
	s_waitcnt lgkmcnt(1)
	v_mfma_f32_16x16x32_bf16 v[46:49], v[42:45], v[90:93], v[26:29]
	s_waitcnt vmcnt(1) lgkmcnt(0)
	v_mfma_f32_16x16x32_bf16 v[26:29], v[54:57], v[94:97], v[66:69]
	s_nop 2
	v_mfma_f32_16x16x32_bf16 v[30:33], v[42:45], v[94:97], v[30:33]
	v_mfma_f32_16x16x32_bf16 v[58:61], v[54:57], v[86:89], v[34:37]
	v_mfma_f32_16x16x32_bf16 v[42:45], v[54:57], v[90:93], v[38:41]
	v_mfma_f32_16x16x32_bf16 v[54:57], v[134:137], v[86:89], v[70:73]
	v_mfma_f32_16x16x32_bf16 v[38:41], v[134:137], v[90:93], v[50:53]
	v_mfma_f32_16x16x32_bf16 v[22:25], v[134:137], v[94:97], v[74:77]
	s_waitcnt vmcnt(0)
	v_mfma_f32_16x16x32_bf16 v[50:53], v[110:113], v[86:89], v[18:21]
	v_mfma_f32_16x16x32_bf16 v[34:37], v[110:113], v[90:93], v[78:81]
	v_mfma_f32_16x16x32_bf16 v[18:21], v[110:113], v[94:97], v[82:85]
	s_cbranch_vccz .LBB0_515
	v_mul_f32_e32 v66, v195, v62
	v_mul_f32_e32 v67, v195, v63
	v_cvt_pk_bf16_f32 v66, v66, v67
	v_mul_f32_e32 v67, v195, v64
	v_mul_f32_e32 v68, v195, v65
	v_cvt_pk_bf16_f32 v67, v67, v68
	global_store_dwordx2 v[138:139], v[66:67], off
	v_mul_f32_e32 v66, v195, v58
	v_mul_f32_e32 v67, v195, v59
	v_cvt_pk_bf16_f32 v66, v66, v67
	v_mul_f32_e32 v67, v195, v60
	v_mul_f32_e32 v68, v195, v61
	v_cvt_pk_bf16_f32 v67, v67, v68
	global_store_dwordx2 v[138:139], v[66:67], off offset:32
	v_mul_f32_e32 v66, v195, v54
	v_mul_f32_e32 v67, v195, v55
	v_cvt_pk_bf16_f32 v66, v66, v67
	v_mul_f32_e32 v67, v195, v56
	v_mul_f32_e32 v68, v195, v57
	v_cvt_pk_bf16_f32 v67, v67, v68
	global_store_dwordx2 v[138:139], v[66:67], off offset:64
	v_mul_f32_e32 v66, v195, v50
	v_mul_f32_e32 v67, v195, v51
	v_cvt_pk_bf16_f32 v66, v66, v67
	v_mul_f32_e32 v67, v195, v52
	v_mul_f32_e32 v68, v195, v53
	v_cvt_pk_bf16_f32 v67, v67, v68
	global_store_dwordx2 v[138:139], v[66:67], off offset:96
	s_mov_b64 s[18:19], 0

; __device__ __forceinline__ float bf2f(bf16_t v) { return __uint_as_float(((unsigned)v) << 16); }
; #define LAS __attribute__((address_space(3)))
; __device__ __forceinline__ void ph_prep(bf16_t* Z, const bf16_t* WUQ, const bf16_t* WUKV, const bf16_t* D64, const float* qkq, const float* qkk,
;                                         bf16_t* Q, bf16_t* Kb, bf16_t* Vb, bf16_t* F1lat, bf16_t* F1ctx, unsigned char* lds_) { PH_IDS;
;     ...
; #pragma unroll
;                     for (int tt = 0; tt < 3; ++tt) { bq[tt] = *(const LAS bf16x8*)(sm + O_KV + rl[tt] * P_KV + (32 * ks + 8 * kq) * 2);
;                         if (pass == 0) {
; #pragma unroll
;                             for (int e = 0; e < 8; ++e) { const float f = bf2f((bf16_t)bq[tt][e]); ssq[tt] += f * f; } } }
.LBB0_545:
	s_waitcnt lgkmcnt(0)
	v_and_b32_e32 v125, 0xffff0000, v82
	v_lshlrev_b32_e32 v124, 16, v82
	v_pk_mul_f32 v[124:125], v[124:125], v[124:125]
	s_nop 0
	v_add_f32_e32 v124, v252, v124
	v_add_f32_e32 v98, v125, v124
	v_and_b32_e32 v125, 0xffff0000, v83
	v_lshlrev_b32_e32 v124, 16, v83
	v_pk_mul_f32 v[124:125], v[124:125], v[124:125]
	s_nop 0
	v_add_f32_e32 v124, v124, v98
	v_add_f32_e32 v98, v125, v124
	v_and_b32_e32 v125, 0xffff0000, v84
	v_lshlrev_b32_e32 v124, 16, v84
	v_pk_mul_f32 v[124:125], v[124:125], v[124:125]
	s_nop 0
	v_add_f32_e32 v124, v124, v98
	v_add_f32_e32 v98, v125, v124
	v_and_b32_e32 v125, 0xffff0000, v85
	v_lshlrev_b32_e32 v124, 16, v85
	v_pk_mul_f32 v[124:125], v[124:125], v[124:125]
	s_nop 0
	v_add_f32_e32 v124, v124, v98
	v_add_f32_e32 v252, v125, v124
	ds_read_b128 v[90:93], v95 offset:128
	s_and_b64 vcc, exec, s[18:19]
	s_cbranch_vccz .LBB0_508
	s_branch .LBB0_509

; __device__ __forceinline__ float bf2f(bf16_t v) { return __uint_as_float(((unsigned)v) << 16); }
; #define LAS __attribute__((address_space(3)))
; __device__ __forceinline__ void ph_prep(bf16_t* Z, const bf16_t* WUQ, const bf16_t* WUKV, const bf16_t* D64, const float* qkq, const float* qkk,
;                                         bf16_t* Q, bf16_t* Kb, bf16_t* Vb, bf16_t* F1lat, bf16_t* F1ctx, unsigned char* lds_) { PH_IDS;
;     ...
; #pragma unroll
;                     for (int tt = 0; tt < 3; ++tt) { bq[tt] = *(const LAS bf16x8*)(sm + O_KV + rl[tt] * P_KV + (32 * ks + 8 * kq) * 2);
;                         if (pass == 0) {
; #pragma unroll
;                             for (int e = 0; e < 8; ++e) { const float f = bf2f((bf16_t)bq[tt][e]); ssq[tt] += f * f; } } }
.LBB0_547:
	s_waitcnt lgkmcnt(0)
	v_and_b32_e32 v125, 0xffff0000, v90
	v_lshlrev_b32_e32 v124, 16, v90
	v_pk_mul_f32 v[124:125], v[124:125], v[124:125]
	s_nop 0
	v_add_f32_e32 v124, v252, v124
	v_add_f32_e32 v98, v125, v124
	v_and_b32_e32 v125, 0xffff0000, v91
	v_lshlrev_b32_e32 v124, 16, v91
	v_pk_mul_f32 v[124:125], v[124:125], v[124:125]
	s_nop 0
	v_add_f32_e32 v124, v124, v98
	v_add_f32_e32 v98, v125, v124
	v_and_b32_e32 v125, 0xffff0000, v92
	v_lshlrev_b32_e32 v124, 16, v92
	v_pk_mul_f32 v[124:125], v[124:125], v[124:125]
	s_nop 0
	v_add_f32_e32 v124, v124, v98
	v_add_f32_e32 v98, v125, v124
	v_and_b32_e32 v125, 0xffff0000, v93
	v_lshlrev_b32_e32 v124, 16, v93
	v_pk_mul_f32 v[124:125], v[124:125], v[124:125]
	s_nop 0
	v_add_f32_e32 v124, v124, v98
	v_add_f32_e32 v252, v125, v124
	ds_read_b128 v[94:97], v95 offset:192
	s_and_b64 vcc, exec, s[18:19]
	s_cbranch_vccz .LBB0_512
	s_branch .LBB0_513

; __device__ __forceinline__ float bf2f(bf16_t v) { return __uint_as_float(((unsigned)v) << 16); }
; #define LAS __attribute__((address_space(3)))
; __device__ __forceinline__ void ph_prep(bf16_t* Z, const bf16_t* WUQ, const bf16_t* WUKV, const bf16_t* D64, const float* qkq, const float* qkk,
;                                         bf16_t* Q, bf16_t* Kb, bf16_t* Vb, bf16_t* F1lat, bf16_t* F1ctx, unsigned char* lds_) { PH_IDS;
;     ...
;             for (int ks = 0; ks < 8; ++ks) {
;                 bf16x8 bq[3], aw[6];
; #pragma unroll
;                 for (int tt = 0; tt < 3; ++tt) { bq[tt] = *(const LAS bf16x8*)(sm + O_QC + rl[tt] * P_QC + (32 * ks + 8 * kq) * 2);
; #pragma unroll
;                     for (int e = 0; e < 8; ++e) { const float f = bf2f((bf16_t)bq[tt][e]); ssq[tt] += f * f; } }
; #pragma unroll
;                 for (int nt = 0; nt < 6; ++nt) aw[nt] = *(const bf16x8*)(WUQ + (size_t)(h * 96 + 16 * nt + c16) * 256 + 32 * ks + 8 * kq);
; #pragma unroll
;                 for (int nt = 0; nt < 6; ++nt)
; #pragma unroll
;                     for (int tt = 0; tt < 3; ++tt) acc[nt][tt] = __builtin_amdgcn_mfma_f32_16x16x32_bf16(aw[nt], bq[tt], acc[nt][tt], 0, 0, 0);
;             }
.LBB0_573:
	v_add_u32_e32 v195, v100, v141
	ds_read_b128 v[90:93], v195
	v_add_u32_e32 v222, v100, v142
	ds_read_b128 v[144:147], v222
	v_add_u32_e32 v223, v100, v140
	ds_read_b128 v[148:151], v223
	s_waitcnt lgkmcnt(2)
	v_lshlrev_b32_e32 v96, 16, v90
	v_fmac_f32_e32 v143, v96, v96
	v_and_b32_e32 v96, 0xffff0000, v90
	v_lshlrev_b32_e32 v97, 16, v91
	v_pk_mul_f32 v[96:97], v[96:97], v[96:97]
	v_lshl_add_u64 v[156:157], v[132:133], 0, s[12:13]
	v_add_f32_e32 v96, v96, v143
	v_add_f32_e32 v138, v97, v96
	v_and_b32_e32 v96, 0xffff0000, v91
	v_lshlrev_b32_e32 v97, 16, v92
	v_pk_mul_f32 v[96:97], v[96:97], v[96:97]
	v_lshl_add_u64 v[248:249], v[130:131], 0, s[12:13]
	v_add_f32_e32 v96, v96, v138
	v_add_f32_e32 v138, v97, v96
	v_and_b32_e32 v96, 0xffff0000, v92
	v_lshlrev_b32_e32 v97, 16, v93
	v_pk_mul_f32 v[96:97], v[96:97], v[96:97]
	v_lshl_add_u64 v[250:251], v[128:129], 0, s[12:13]
	v_add_f32_e32 v96, v96, v138
	v_add_f32_e32 v143, v97, v96
	v_and_b32_e32 v96, 0xffff0000, v93
	v_fmac_f32_e32 v143, v96, v96
	s_waitcnt lgkmcnt(1)
	v_lshlrev_b32_e32 v97, 16, v144
	s_waitcnt lgkmcnt(0)
	v_lshlrev_b32_e32 v96, 16, v148
	v_pk_fma_f32 v[94:95], v[96:97], v[96:97], v[94:95]
	v_and_b32_e32 v97, 0xffff0000, v144
	v_and_b32_e32 v96, 0xffff0000, v148
	v_pk_fma_f32 v[94:95], v[96:97], v[96:97], v[94:95]
	v_lshlrev_b32_e32 v97, 16, v145
	v_lshlrev_b32_e32 v96, 16, v149
	v_pk_fma_f32 v[94:95], v[96:97], v[96:97], v[94:95]
	v_and_b32_e32 v97, 0xffff0000, v145
	v_and_b32_e32 v96, 0xffff0000, v149
	v_pk_fma_f32 v[94:95], v[96:97], v[96:97], v[94:95]
	v_lshlrev_b32_e32 v97, 16, v146
	v_lshlrev_b32_e32 v96, 16, v150
	v_pk_fma_f32 v[94:95], v[96:97], v[96:97], v[94:95]
	v_and_b32_e32 v97, 0xffff0000, v146
	v_and_b32_e32 v96, 0xffff0000, v150
	v_pk_fma_f32 v[94:95], v[96:97], v[96:97], v[94:95]
	v_lshlrev_b32_e32 v97, 16, v147
	v_lshlrev_b32_e32 v96, 16, v151
	v_pk_fma_f32 v[94:95], v[96:97], v[96:97], v[94:95]
	v_and_b32_e32 v97, 0xffff0000, v147
	v_and_b32_e32 v96, 0xffff0000, v151
	v_pk_fma_f32 v[94:95], v[96:97], v[96:97], v[94:95]
	v_lshl_add_u64 v[96:97], v[136:137], 0, s[12:13]
	v_add_co_u32_e32 v96, vcc, s54, v96
	v_lshl_add_u64 v[138:139], v[134:135], 0, s[12:13]
	s_nop 0
	v_addc_co_u32_e32 v97, vcc, 0, v97, vcc
	v_add_co_u32_e32 v138, vcc, s54, v138
	v_lshl_add_u64 v[252:253], v[126:127], 0, s[12:13]
	s_nop 0
	v_addc_co_u32_e32 v139, vcc, 0, v139, vcc
	v_add_co_u32_e32 v156, vcc, s54, v156
	v_addc_co_u32_e32 v157, vcc, 0, v157, vcc
	v_add_co_u32_e32 v216, vcc, s54, v248
	s_nop 0
	v_addc_co_u32_e32 v217, vcc, 0, v249, vcc
	v_add_co_u32_e32 v218, vcc, s54, v250
	s_nop 0
	v_addc_co_u32_e32 v219, vcc, 0, v251, vcc
	v_add_co_u32_e32 v220, vcc, s54, v252
	s_nop 0
	v_addc_co_u32_e32 v221, vcc, 0, v253, vcc
	s_cmp_lg_u32 s12, 0
	s_cbranch_scc1 .Lqpf_a_L0
	global_load_dwordx4 v[152:155], v[96:97], off
	global_load_dwordx4 v[196:199], v[138:139], off
	global_load_dwordx4 v[200:203], v[156:157], off
	global_load_dwordx4 v[204:207], v[216:217], off
	global_load_dwordx4 v[208:211], v[218:219], off
	global_load_dwordx4 v[212:215], v[220:221], off
.Lqpf_a_L0:
	global_load_dwordx4 v[2:5], v[96:97], off offset:64
	global_load_dwordx4 v[6:9], v[138:139], off offset:64
	global_load_dwordx4 v[10:13], v[156:157], off offset:64
	global_load_dwordx4 v[14:17], v[216:217], off offset:64
	global_load_dwordx4 v[102:105], v[218:219], off offset:64
	global_load_dwordx4 v[106:109], v[220:221], off offset:64
	s_add_u32 s12, s12, 0x100
	s_addc_u32 s13, s13, 0
	v_add_u32_e32 v100, 0x100, v100
	s_cmpk_eq_i32 s12, 0x200
	s_waitcnt vmcnt(6)
	v_mfma_f32_16x16x32_bf16 v[86:89], v[152:155], v[90:93], v[86:89]
	v_mfma_f32_16x16x32_bf16 v[82:85], v[196:199], v[90:93], v[82:85]
	v_mfma_f32_16x16x32_bf16 v[78:81], v[200:203], v[90:93], v[78:81]
	v_mfma_f32_16x16x32_bf16 v[74:77], v[204:207], v[90:93], v[74:77]
	v_mfma_f32_16x16x32_bf16 v[70:73], v[208:211], v[90:93], v[70:73]
	v_mfma_f32_16x16x32_bf16 v[66:69], v[212:215], v[90:93], v[66:69]
	ds_read_b128 v[90:93], v195 offset:64
	v_mfma_f32_16x16x32_bf16 v[62:65], v[152:155], v[144:147], v[62:65]
	v_mfma_f32_16x16x32_bf16 v[58:61], v[196:199], v[144:147], v[58:61]
	v_mfma_f32_16x16x32_bf16 v[54:57], v[200:203], v[144:147], v[54:57]
	v_mfma_f32_16x16x32_bf16 v[46:49], v[204:207], v[144:147], v[46:49]
	v_mfma_f32_16x16x32_bf16 v[50:53], v[208:211], v[144:147], v[50:53]
	v_mfma_f32_16x16x32_bf16 v[42:45], v[212:215], v[144:147], v[42:45]
	s_waitcnt lgkmcnt(0)
	v_lshlrev_b32_e32 v144, 16, v90
	v_fmac_f32_e32 v143, v144, v144
	v_and_b32_e32 v144, 0xffff0000, v90
	v_lshlrev_b32_e32 v145, 16, v91
	v_pk_mul_f32 v[144:145], v[144:145], v[144:145]
	v_mfma_f32_16x16x32_bf16 v[38:41], v[152:155], v[148:151], v[38:41]
	v_add_f32_e32 v143, v144, v143
	v_add_f32_e32 v143, v145, v143
	v_and_b32_e32 v144, 0xffff0000, v91
	v_lshlrev_b32_e32 v145, 16, v92
	v_pk_mul_f32 v[144:145], v[144:145], v[144:145]
	v_mfma_f32_16x16x32_bf16 v[34:37], v[196:199], v[148:151], v[34:37]
	v_add_f32_e32 v143, v144, v143
	v_add_f32_e32 v143, v145, v143
	v_and_b32_e32 v144, 0xffff0000, v92
	v_lshlrev_b32_e32 v145, 16, v93
	v_pk_mul_f32 v[144:145], v[144:145], v[144:145]
	v_mfma_f32_16x16x32_bf16 v[30:33], v[200:203], v[148:151], v[30:33]
	v_add_f32_e32 v143, v144, v143
	v_add_f32_e32 v143, v145, v143
	v_and_b32_e32 v144, 0xffff0000, v93
	v_mfma_f32_16x16x32_bf16 v[22:25], v[204:207], v[148:151], v[22:25]
	v_fmac_f32_e32 v143, v144, v144
	v_mfma_f32_16x16x32_bf16 v[26:29], v[208:211], v[148:151], v[26:29]
	v_mfma_f32_16x16x32_bf16 v[18:21], v[212:215], v[148:151], v[18:21]
	ds_read_b128 v[144:147], v222 offset:64
	ds_read_b128 v[148:151], v223 offset:64
	s_waitcnt lgkmcnt(1)
; __device__ __forceinline__ float bf2f(bf16_t v) { return __uint_as_float(((unsigned)v) << 16); }
; #define LAS __attribute__((address_space(3)))
; __device__ __forceinline__ void ph_prep(bf16_t* Z, const bf16_t* WUQ, const bf16_t* WUKV, const bf16_t* D64, const float* qkq, const float* qkk,
;                                         bf16_t* Q, bf16_t* Kb, bf16_t* Vb, bf16_t* F1lat, bf16_t* F1ctx, unsigned char* lds_) { PH_IDS;
;     ...
;             for (int ks = 0; ks < 8; ++ks) {
;                 bf16x8 bq[3], aw[6];
; #pragma unroll
;                 for (int tt = 0; tt < 3; ++tt) { bq[tt] = *(const LAS bf16x8*)(sm + O_QC + rl[tt] * P_QC + (32 * ks + 8 * kq) * 2);
; #pragma unroll
;                     for (int e = 0; e < 8; ++e) { const float f = bf2f((bf16_t)bq[tt][e]); ssq[tt] += f * f; } }
; #pragma unroll
;                 for (int nt = 0; nt < 6; ++nt) aw[nt] = *(const bf16x8*)(WUQ + (size_t)(h * 96 + 16 * nt + c16) * 256 + 32 * ks + 8 * kq);
; #pragma unroll
;                 for (int nt = 0; nt < 6; ++nt)
; #pragma unroll
;                     for (int tt = 0; tt < 3; ++tt) acc[nt][tt] = __builtin_amdgcn_mfma_f32_16x16x32_bf16(aw[nt], bq[tt], acc[nt][tt], 0, 0, 0);
;             }
	v_lshlrev_b32_e32 v253, 16, v144
	s_waitcnt lgkmcnt(0)
	v_lshlrev_b32_e32 v252, 16, v148
	v_pk_fma_f32 v[94:95], v[252:253], v[252:253], v[94:95]
	v_and_b32_e32 v253, 0xffff0000, v144
	v_and_b32_e32 v252, 0xffff0000, v148
	v_pk_fma_f32 v[94:95], v[252:253], v[252:253], v[94:95]
	v_lshlrev_b32_e32 v253, 16, v145
	v_lshlrev_b32_e32 v252, 16, v149
	v_pk_fma_f32 v[94:95], v[252:253], v[252:253], v[94:95]
	v_and_b32_e32 v253, 0xffff0000, v145
	v_and_b32_e32 v252, 0xffff0000, v149
	v_pk_fma_f32 v[94:95], v[252:253], v[252:253], v[94:95]
	v_lshlrev_b32_e32 v253, 16, v146
	v_lshlrev_b32_e32 v252, 16, v150
	v_pk_fma_f32 v[94:95], v[252:253], v[252:253], v[94:95]
	v_and_b32_e32 v253, 0xffff0000, v146
	v_and_b32_e32 v252, 0xffff0000, v150
	v_pk_fma_f32 v[94:95], v[252:253], v[252:253], v[94:95]
	v_lshlrev_b32_e32 v253, 16, v147
	v_lshlrev_b32_e32 v252, 16, v151
	v_pk_fma_f32 v[94:95], v[252:253], v[252:253], v[94:95]
	v_and_b32_e32 v253, 0xffff0000, v147
	v_and_b32_e32 v252, 0xffff0000, v151
	v_pk_fma_f32 v[94:95], v[252:253], v[252:253], v[94:95]
	global_load_dwordx4 v[152:155], v[96:97], off offset:128
	global_load_dwordx4 v[196:199], v[138:139], off offset:128
	global_load_dwordx4 v[200:203], v[156:157], off offset:128
	global_load_dwordx4 v[204:207], v[216:217], off offset:128
	global_load_dwordx4 v[208:211], v[218:219], off offset:128
	global_load_dwordx4 v[212:215], v[220:221], off offset:128
	s_waitcnt vmcnt(6)
	v_mfma_f32_16x16x32_bf16 v[86:89], v[2:5], v[90:93], v[86:89]
	v_mfma_f32_16x16x32_bf16 v[82:85], v[6:9], v[90:93], v[82:85]
	v_mfma_f32_16x16x32_bf16 v[78:81], v[10:13], v[90:93], v[78:81]
	v_mfma_f32_16x16x32_bf16 v[74:77], v[14:17], v[90:93], v[74:77]
	v_mfma_f32_16x16x32_bf16 v[70:73], v[102:105], v[90:93], v[70:73]
	v_mfma_f32_16x16x32_bf16 v[66:69], v[106:109], v[90:93], v[66:69]
	ds_read_b128 v[90:93], v195 offset:128
	v_mfma_f32_16x16x32_bf16 v[62:65], v[2:5], v[144:147], v[62:65]
	v_mfma_f32_16x16x32_bf16 v[58:61], v[6:9], v[144:147], v[58:61]
	v_mfma_f32_16x16x32_bf16 v[54:57], v[10:13], v[144:147], v[54:57]
	v_mfma_f32_16x16x32_bf16 v[46:49], v[14:17], v[144:147], v[46:49]
	v_mfma_f32_16x16x32_bf16 v[50:53], v[102:105], v[144:147], v[50:53]
	v_mfma_f32_16x16x32_bf16 v[42:45], v[106:109], v[144:147], v[42:45]
	s_waitcnt lgkmcnt(0)
	v_lshlrev_b32_e32 v144, 16, v90
	v_fmac_f32_e32 v143, v144, v144
	v_and_b32_e32 v144, 0xffff0000, v90
	v_lshlrev_b32_e32 v145, 16, v91
	v_pk_mul_f32 v[144:145], v[144:145], v[144:145]
	v_mfma_f32_16x16x32_bf16 v[38:41], v[2:5], v[148:151], v[38:41]
	v_add_f32_e32 v143, v144, v143
	v_add_f32_e32 v143, v145, v143
	v_and_b32_e32 v144, 0xffff0000, v91
	v_lshlrev_b32_e32 v145, 16, v92
	v_pk_mul_f32 v[144:145], v[144:145], v[144:145]
	v_mfma_f32_16x16x32_bf16 v[34:37], v[6:9], v[148:151], v[34:37]
	v_add_f32_e32 v143, v144, v143
	v_add_f32_e32 v143, v145, v143
	v_and_b32_e32 v144, 0xffff0000, v92
	v_lshlrev_b32_e32 v145, 16, v93
	v_pk_mul_f32 v[144:145], v[144:145], v[144:145]
	v_mfma_f32_16x16x32_bf16 v[30:33], v[10:13], v[148:151], v[30:33]
	v_add_f32_e32 v143, v144, v143
	v_add_f32_e32 v143, v145, v143
	v_and_b32_e32 v144, 0xffff0000, v93
	v_mfma_f32_16x16x32_bf16 v[22:25], v[14:17], v[148:151], v[22:25]
	v_fmac_f32_e32 v143, v144, v144
	v_mfma_f32_16x16x32_bf16 v[26:29], v[102:105], v[148:151], v[26:29]
	v_mfma_f32_16x16x32_bf16 v[18:21], v[106:109], v[148:151], v[18:21]
	ds_read_b128 v[144:147], v222 offset:128
	ds_read_b128 v[148:151], v223 offset:128
	s_waitcnt lgkmcnt(1)
	v_lshlrev_b32_e32 v253, 16, v144
	s_waitcnt lgkmcnt(0)
	v_lshlrev_b32_e32 v252, 16, v148
	v_pk_fma_f32 v[94:95], v[252:253], v[252:253], v[94:95]
	v_and_b32_e32 v253, 0xffff0000, v144
	v_and_b32_e32 v252, 0xffff0000, v148
	v_pk_fma_f32 v[94:95], v[252:253], v[252:253], v[94:95]
	v_lshlrev_b32_e32 v253, 16, v145
	v_lshlrev_b32_e32 v252, 16, v149
	v_pk_fma_f32 v[94:95], v[252:253], v[252:253], v[94:95]
	v_and_b32_e32 v253, 0xffff0000, v145
	v_and_b32_e32 v252, 0xffff0000, v149
	v_pk_fma_f32 v[94:95], v[252:253], v[252:253], v[94:95]
	v_lshlrev_b32_e32 v253, 16, v146
	v_lshlrev_b32_e32 v252, 16, v150
	v_pk_fma_f32 v[94:95], v[252:253], v[252:253], v[94:95]
	v_and_b32_e32 v253, 0xffff0000, v146
	v_and_b32_e32 v252, 0xffff0000, v150
	v_pk_fma_f32 v[94:95], v[252:253], v[252:253], v[94:95]
	v_lshlrev_b32_e32 v253, 16, v147
	v_lshlrev_b32_e32 v252, 16, v151
	v_pk_fma_f32 v[94:95], v[252:253], v[252:253], v[94:95]
	v_and_b32_e32 v253, 0xffff0000, v147
	v_and_b32_e32 v252, 0xffff0000, v151
	v_pk_fma_f32 v[94:95], v[252:253], v[252:253], v[94:95]
	global_load_dwordx4 v[2:5], v[96:97], off offset:192
	global_load_dwordx4 v[6:9], v[138:139], off offset:192
	global_load_dwordx4 v[10:13], v[156:157], off offset:192
	global_load_dwordx4 v[14:17], v[216:217], off offset:192
	global_load_dwordx4 v[102:105], v[218:219], off offset:192
	global_load_dwordx4 v[106:109], v[220:221], off offset:192
	s_waitcnt vmcnt(6)
; __device__ __forceinline__ float bf2f(bf16_t v) { return __uint_as_float(((unsigned)v) << 16); }
; #define LAS __attribute__((address_space(3)))
; __device__ __forceinline__ void ph_prep(bf16_t* Z, const bf16_t* WUQ, const bf16_t* WUKV, const bf16_t* D64, const float* qkq, const float* qkk,
;                                         bf16_t* Q, bf16_t* Kb, bf16_t* Vb, bf16_t* F1lat, bf16_t* F1ctx, unsigned char* lds_) { PH_IDS;
;     ...
;             for (int ks = 0; ks < 8; ++ks) {
;                 bf16x8 bq[3], aw[6];
; #pragma unroll
;                 for (int tt = 0; tt < 3; ++tt) { bq[tt] = *(const LAS bf16x8*)(sm + O_QC + rl[tt] * P_QC + (32 * ks + 8 * kq) * 2);
; #pragma unroll
;                     for (int e = 0; e < 8; ++e) { const float f = bf2f((bf16_t)bq[tt][e]); ssq[tt] += f * f; } }
; #pragma unroll
;                 for (int nt = 0; nt < 6; ++nt) aw[nt] = *(const bf16x8*)(WUQ + (size_t)(h * 96 + 16 * nt + c16) * 256 + 32 * ks + 8 * kq);
; #pragma unroll
;                 for (int nt = 0; nt < 6; ++nt)
; #pragma unroll
;                     for (int tt = 0; tt < 3; ++tt) acc[nt][tt] = __builtin_amdgcn_mfma_f32_16x16x32_bf16(aw[nt], bq[tt], acc[nt][tt], 0, 0, 0);
;             }
	v_mfma_f32_16x16x32_bf16 v[86:89], v[152:155], v[90:93], v[86:89]
	v_mfma_f32_16x16x32_bf16 v[82:85], v[196:199], v[90:93], v[82:85]
	v_mfma_f32_16x16x32_bf16 v[78:81], v[200:203], v[90:93], v[78:81]
	v_mfma_f32_16x16x32_bf16 v[74:77], v[204:207], v[90:93], v[74:77]
	v_mfma_f32_16x16x32_bf16 v[70:73], v[208:211], v[90:93], v[70:73]
	v_mfma_f32_16x16x32_bf16 v[66:69], v[212:215], v[90:93], v[66:69]
	ds_read_b128 v[90:93], v195 offset:192
	v_mfma_f32_16x16x32_bf16 v[62:65], v[152:155], v[144:147], v[62:65]
	v_mfma_f32_16x16x32_bf16 v[58:61], v[196:199], v[144:147], v[58:61]
	v_mfma_f32_16x16x32_bf16 v[54:57], v[200:203], v[144:147], v[54:57]
	v_mfma_f32_16x16x32_bf16 v[46:49], v[204:207], v[144:147], v[46:49]
	v_mfma_f32_16x16x32_bf16 v[50:53], v[208:211], v[144:147], v[50:53]
	v_mfma_f32_16x16x32_bf16 v[42:45], v[212:215], v[144:147], v[42:45]
	s_waitcnt lgkmcnt(0)
	v_lshlrev_b32_e32 v144, 16, v90
	v_fmac_f32_e32 v143, v144, v144
	v_and_b32_e32 v144, 0xffff0000, v90
	v_lshlrev_b32_e32 v145, 16, v91
	v_pk_mul_f32 v[144:145], v[144:145], v[144:145]
	v_mfma_f32_16x16x32_bf16 v[38:41], v[152:155], v[148:151], v[38:41]
	v_add_f32_e32 v143, v144, v143
	v_add_f32_e32 v143, v145, v143
	v_and_b32_e32 v144, 0xffff0000, v91
	v_lshlrev_b32_e32 v145, 16, v92
	v_pk_mul_f32 v[144:145], v[144:145], v[144:145]
	v_mfma_f32_16x16x32_bf16 v[34:37], v[196:199], v[148:151], v[34:37]
	v_add_f32_e32 v143, v144, v143
	v_add_f32_e32 v143, v145, v143
	v_and_b32_e32 v144, 0xffff0000, v92
	v_lshlrev_b32_e32 v145, 16, v93
	v_pk_mul_f32 v[144:145], v[144:145], v[144:145]
	v_mfma_f32_16x16x32_bf16 v[30:33], v[200:203], v[148:151], v[30:33]
	v_add_f32_e32 v143, v144, v143
	v_add_f32_e32 v143, v145, v143
	v_and_b32_e32 v144, 0xffff0000, v93
	v_mfma_f32_16x16x32_bf16 v[22:25], v[204:207], v[148:151], v[22:25]
	v_fmac_f32_e32 v143, v144, v144
	v_mfma_f32_16x16x32_bf16 v[26:29], v[208:211], v[148:151], v[26:29]
	v_mfma_f32_16x16x32_bf16 v[18:21], v[212:215], v[148:151], v[18:21]
	ds_read_b128 v[144:147], v222 offset:192
	ds_read_b128 v[148:151], v223 offset:192
	s_waitcnt lgkmcnt(1)
	v_lshlrev_b32_e32 v253, 16, v144
	s_waitcnt lgkmcnt(0)
	v_lshlrev_b32_e32 v252, 16, v148
	v_pk_fma_f32 v[94:95], v[252:253], v[252:253], v[94:95]
	v_and_b32_e32 v253, 0xffff0000, v144
	v_and_b32_e32 v252, 0xffff0000, v148
	v_pk_fma_f32 v[94:95], v[252:253], v[252:253], v[94:95]
	v_lshlrev_b32_e32 v253, 16, v145
	v_lshlrev_b32_e32 v252, 16, v149
	v_pk_fma_f32 v[94:95], v[252:253], v[252:253], v[94:95]
	v_and_b32_e32 v253, 0xffff0000, v145
	v_and_b32_e32 v252, 0xffff0000, v149
	v_pk_fma_f32 v[94:95], v[252:253], v[252:253], v[94:95]
	v_lshlrev_b32_e32 v253, 16, v146
	v_lshlrev_b32_e32 v252, 16, v150
	v_pk_fma_f32 v[94:95], v[252:253], v[252:253], v[94:95]
	v_and_b32_e32 v253, 0xffff0000, v146
	v_and_b32_e32 v252, 0xffff0000, v150
	v_pk_fma_f32 v[94:95], v[252:253], v[252:253], v[94:95]
	v_lshlrev_b32_e32 v253, 16, v147
	v_lshlrev_b32_e32 v252, 16, v151
	v_pk_fma_f32 v[94:95], v[252:253], v[252:253], v[94:95]
	v_and_b32_e32 v253, 0xffff0000, v147
	v_and_b32_e32 v252, 0xffff0000, v151
	v_pk_fma_f32 v[94:95], v[252:253], v[252:253], v[94:95]
	s_cmpk_eq_i32 s12, 0x200
	s_cbranch_scc1 .Lqpf_b_L0
	global_load_dwordx4 v[152:155], v[96:97], off offset:256
	global_load_dwordx4 v[196:199], v[138:139], off offset:256
	global_load_dwordx4 v[200:203], v[156:157], off offset:256
	global_load_dwordx4 v[204:207], v[216:217], off offset:256
	global_load_dwordx4 v[208:211], v[218:219], off offset:256
	global_load_dwordx4 v[212:215], v[220:221], off offset:256
	s_waitcnt vmcnt(6)
	s_branch .Lqpf_c_L0

; __device__ __forceinline__ float bf2f(bf16_t v) { return __uint_as_float(((unsigned)v) << 16); }
; #define LAS __attribute__((address_space(3)))
; __device__ __forceinline__ void ph_prep(bf16_t* Z, const bf16_t* WUQ, const bf16_t* WUKV, const bf16_t* D64, const float* qkq, const float* qkk,
;                                         bf16_t* Q, bf16_t* Kb, bf16_t* Vb, bf16_t* F1lat, bf16_t* F1ctx, unsigned char* lds_) { PH_IDS;
;     ...
;             for (int ks = 0; ks < 8; ++ks) {
;                 bf16x8 bq[3], aw[6];
; #pragma unroll
;                 for (int tt = 0; tt < 3; ++tt) { bq[tt] = *(const LAS bf16x8*)(sm + O_QC + rl[tt] * P_QC + (32 * ks + 8 * kq) * 2);
; #pragma unroll
;                     for (int e = 0; e < 8; ++e) { const float f = bf2f((bf16_t)bq[tt][e]); ssq[tt] += f * f; } }
; #pragma unroll
;                 for (int nt = 0; nt < 6; ++nt) aw[nt] = *(const bf16x8*)(WUQ + (size_t)(h * 96 + 16 * nt + c16) * 256 + 32 * ks + 8 * kq);
; #pragma unroll
;                 for (int nt = 0; nt < 6; ++nt)
; #pragma unroll
;                     for (int tt = 0; tt < 3; ++tt) acc[nt][tt] = __builtin_amdgcn_mfma_f32_16x16x32_bf16(aw[nt], bq[tt], acc[nt][tt], 0, 0, 0);
;             }
;     ...
;             for (int tt = 0; tt < 3; ++tt) {
;                 float s1 = ssq[tt]; s1 += __shfl_xor(s1, 16); s1 += __shfl_xor(s1, 32);
;                 const float rstd = rsqrtf(s1 * (1.f / 256) + EPS);
;                 float ss = 0.f;
; #pragma unroll
;                 for (int nt = 0; nt < 6; ++nt)
; #pragma unroll
;                     for (int r = 0; r < 4; ++r) ss += acc[nt][tt][r] * acc[nt][tt][r];
;                 ss += __shfl_xor(ss, 16); ss += __shfl_xor(ss, 32);
;                 const float fac = rstd * rsqrtf(rstd * rstd * ss * (1.f / 96) + EPS) * 0.14724727430627066f;
;                 const int row = rowc[tt]; const bool lat = row < RL; const int b = row_batch(row), t = lat ? (row & 2047) : ((row - RL) & 255), qi = lat ? t : 2048 + t;
;                 bf16_t* qo = Q + ((size_t)(b * 4 + h) * 2304 + qi) * 96 + 4 * kq;
; #pragma unroll
;                 for (int nt = 0; nt < 6; ++nt) {
;                     const f32x4 w = *(const f32x4*)(qkq + 16 * nt + 4 * kq);
;                     float v[4];
; #pragma unroll
;                     for (int r = 0; r < 4; ++r) v[r] = acc[nt][tt][r] * fac * w[r];
.Lqpf_c_L0:
	v_mfma_f32_16x16x32_bf16 v[86:89], v[2:5], v[90:93], v[86:89]
	v_mfma_f32_16x16x32_bf16 v[62:65], v[2:5], v[144:147], v[62:65]
	v_mfma_f32_16x16x32_bf16 v[38:41], v[2:5], v[148:151], v[38:41]
	v_mfma_f32_16x16x32_bf16 v[82:85], v[6:9], v[90:93], v[82:85]
	v_mfma_f32_16x16x32_bf16 v[58:61], v[6:9], v[144:147], v[58:61]
	v_mfma_f32_16x16x32_bf16 v[34:37], v[6:9], v[148:151], v[34:37]
	v_mfma_f32_16x16x32_bf16 v[78:81], v[10:13], v[90:93], v[78:81]
	v_mfma_f32_16x16x32_bf16 v[54:57], v[10:13], v[144:147], v[54:57]
	v_mfma_f32_16x16x32_bf16 v[30:33], v[10:13], v[148:151], v[30:33]
	v_mfma_f32_16x16x32_bf16 v[74:77], v[14:17], v[90:93], v[74:77]
	v_mfma_f32_16x16x32_bf16 v[46:49], v[14:17], v[144:147], v[46:49]
	v_mfma_f32_16x16x32_bf16 v[22:25], v[14:17], v[148:151], v[22:25]
	v_mfma_f32_16x16x32_bf16 v[70:73], v[102:105], v[90:93], v[70:73]
	v_mfma_f32_16x16x32_bf16 v[50:53], v[102:105], v[144:147], v[50:53]
	v_mfma_f32_16x16x32_bf16 v[26:29], v[102:105], v[148:151], v[26:29]
	v_mfma_f32_16x16x32_bf16 v[66:69], v[106:109], v[90:93], v[66:69]
	v_mfma_f32_16x16x32_bf16 v[42:45], v[106:109], v[144:147], v[42:45]
	v_mfma_f32_16x16x32_bf16 v[18:21], v[106:109], v[148:151], v[18:21]
	s_cbranch_scc0 .LBB0_573
	v_mov_b64_e32 v[144:145], v[224:225]
	v_mov_b64_e32 v[146:147], v[226:227]
	v_mul_f32_e32 v150, v87, v87
	v_fmac_f32_e32 v150, v86, v86
	v_fmac_f32_e32 v150, v88, v88
	v_fmac_f32_e32 v150, v89, v89
	v_fmac_f32_e32 v150, v82, v82
	v_fmac_f32_e32 v150, v83, v83
	v_fmac_f32_e32 v150, v84, v84
	v_fmac_f32_e32 v150, v85, v85
	v_fmac_f32_e32 v150, v78, v78
	v_and_b32_e32 v91, 64, v179
	v_fmac_f32_e32 v150, v79, v79
	v_xor_b32_e32 v90, 16, v179
	v_add_u32_e32 v91, 64, v91
	v_fmac_f32_e32 v150, v80, v80
	v_cmp_lt_i32_e64 s[12:13], v90, v91
	v_fmac_f32_e32 v150, v81, v81
	v_xor_b32_e32 v100, 32, v179
	v_cndmask_b32_e64 v90, v179, v90, s[12:13]
	v_fmac_f32_e32 v150, v74, v74
	v_cmp_lt_i32_e64 s[12:13], v100, v91
	v_lshlrev_b32_e32 v91, 2, v90
	v_fmac_f32_e32 v150, v75, v75
	ds_bpermute_b32 v153, v91, v143
	v_fmac_f32_e32 v150, v76, v76
	v_pk_mul_f32 v[96:97], v[70:71], v[70:71]
	v_fmac_f32_e32 v150, v77, v77
	v_add_f32_e32 v96, v96, v150
	v_pk_mul_f32 v[92:93], v[72:73], v[72:73]
	v_add_f32_e32 v96, v97, v96
	v_cndmask_b32_e64 v100, v179, v100, s[12:13]
	v_add_f32_e32 v92, v92, v96
	v_pk_mul_f32 v[148:149], v[66:67], v[66:67]
	v_lshlrev_b32_e32 v90, 2, v100
	s_waitcnt lgkmcnt(0)
	v_add_f32_e32 v143, v143, v153
	v_add_f32_e32 v92, v93, v92
	ds_bpermute_b32 v153, v90, v143
	v_add_f32_e32 v92, v148, v92
	v_pk_mul_f32 v[138:139], v[68:69], v[68:69]
	v_add_f32_e32 v92, v149, v92
	v_add_f32_e32 v92, v138, v92
	v_add_f32_e32 v92, v139, v92
	ds_bpermute_b32 v93, v91, v92
	s_waitcnt lgkmcnt(1)
	v_add_f32_e32 v143, v143, v153
	v_fmamk_f32 v143, v143, 0x3b800000, v175
	v_mul_f32_e32 v96, 0x4b800000, v143
	v_cmp_gt_f32_e64 s[12:13], s53, v143
	v_cmp_gt_i32_e32 vcc, s50, v192
	s_waitcnt lgkmcnt(0)
	v_add_f32_e32 v97, v92, v93
	v_cndmask_b32_e64 v96, v143, v96, s[12:13]
	v_cndmask_b32_e32 v152, v177, v178, vcc
	v_rsq_f32_e32 v96, v96
	v_and_b32_e32 v152, v152, v192
	ds_bpermute_b32 v138, v90, v97
	v_cndmask_b32_e32 v151, v194, v193, vcc
	v_or_b32_e32 v100, 0x800, v152
	v_lshl_add_u32 v151, v151, 2, s29
	v_cndmask_b32_e32 v100, v100, v152, vcc
	v_mad_i64_i32 v[92:93], s[14:15], v151, s51, v[100:101]
	v_mul_f32_e32 v100, 0x45800000, v96
	v_cndmask_b32_e64 v100, v96, v100, s[12:13]
	v_mul_f32_e32 v96, v100, v100
	s_waitcnt lgkmcnt(0)
	v_add_f32_e32 v97, v97, v138
	v_mul_f32_e32 v96, v97, v96
	v_fmamk_f32 v96, v96, 0x3c2aaaab, v175
	v_mul_f32_e32 v97, 0x4b800000, v96
	v_cmp_gt_f32_e64 s[12:13], s53, v96
	s_nop 1
	v_cndmask_b32_e64 v96, v96, v97, s[12:13]
	v_rsq_f32_e32 v138, v96
	v_mad_u64_u32 v[96:97], s[14:15], v92, s52, v[110:111]
	v_mad_i32_i24 v97, v93, s52, v97
	v_mul_f32_e32 v92, 0x45800000, v138
	v_cndmask_b32_e64 v92, v138, v92, s[12:13]
	v_mul_f32_e32 v92, v100, v92
	v_mul_f32_e32 v92, 0x3e16c7fd, v92
	v_mul_f32_e32 v86, v86, v92
	v_mul_f32_e32 v87, v87, v92
	v_mul_f32_e32 v86, v144, v86
	v_mul_f32_e32 v87, v145, v87
	v_mul_f32_e32 v88, v88, v92
	v_mul_f32_e32 v89, v89, v92
	v_mul_f32_e32 v88, v146, v88
	v_mul_f32_e32 v89, v147, v89
	v_cvt_pk_bf16_f32 v86, v86, v87
	v_cvt_pk_bf16_f32 v87, v88, v89
	global_store_dwordx2 v[96:97], v[86:87], off
	v_mov_b64_e32 v[86:87], v[228:229]
	v_mov_b64_e32 v[88:89], v[230:231]
	v_mul_f32_e32 v82, v82, v92
	v_mul_f32_e32 v83, v83, v92
	v_mul_f32_e32 v84, v84, v92
	v_mul_f32_e32 v85, v85, v92
	v_mul_f32_e32 v78, v78, v92
	v_mul_f32_e32 v79, v79, v92
	v_mul_f32_e32 v80, v80, v92
	v_mul_f32_e32 v81, v81, v92
	v_mul_f32_e32 v74, v74, v92
	v_mul_f32_e32 v75, v75, v92
	v_mul_f32_e32 v76, v76, v92
	v_mul_f32_e32 v77, v77, v92
	v_mul_f32_e32 v70, v70, v92
	v_mul_f32_e32 v71, v71, v92
	v_mul_f32_e32 v72, v72, v92
	v_mul_f32_e32 v73, v73, v92
	v_mul_f32_e32 v66, v66, v92
	v_mul_f32_e32 v67, v67, v92
	v_mul_f32_e32 v68, v68, v92
	v_mul_f32_e32 v69, v69, v92
	v_mul_f32_e32 v82, v86, v82
	v_mul_f32_e32 v83, v87, v83
	v_mul_f32_e32 v84, v88, v84
	v_mul_f32_e32 v85, v89, v85
	v_cvt_pk_bf16_f32 v82, v82, v83
	v_cvt_pk_bf16_f32 v83, v84, v85
	global_store_dwordx2 v[96:97], v[82:83], off offset:32
	v_mov_b64_e32 v[82:83], v[232:233]
	v_mov_b64_e32 v[84:85], v[234:235]
	v_mul_f32_e32 v78, v82, v78
	v_mul_f32_e32 v79, v83, v79
	v_mul_f32_e32 v80, v84, v80
	v_mul_f32_e32 v81, v85, v81
	v_cvt_pk_bf16_f32 v78, v78, v79
	v_cvt_pk_bf16_f32 v79, v80, v81
	global_store_dwordx2 v[96:97], v[78:79], off offset:64
	v_mov_b64_e32 v[78:79], v[236:237]
	v_mov_b64_e32 v[80:81], v[238:239]
	v_mul_f32_e32 v74, v78, v74
	v_mul_f32_e32 v75, v79, v75
	v_mul_f32_e32 v76, v80, v76
	v_mul_f32_e32 v77, v81, v77
	v_cvt_pk_bf16_f32 v74, v74, v75
	v_cvt_pk_bf16_f32 v75, v76, v77
	global_store_dwordx2 v[96:97], v[74:75], off offset:96
	v_mov_b64_e32 v[74:75], v[240:241]
	v_mov_b64_e32 v[76:77], v[242:243]
	v_lshrrev_b32_e32 v78, 6, v152
	v_cvt_f32_ubyte0_e32 v78, v78
	v_mul_f32_e32 v79, v167, v78
	v_mul_f32_e32 v80, v166, v78
	v_mul_f32_e32 v81, v165, v78
	v_mul_f32_e32 v78, v164, v78
	v_mul_f32_e32 v81, 0.15915494, v81
	v_mul_f32_e32 v78, 0.15915494, v78
	v_mul_f32_e32 v79, 0.15915494, v79
	v_mul_f32_e32 v80, 0.15915494, v80
	v_cos_f32_e32 v84, v81
	v_sin_f32_e32 v81, v81
	v_cos_f32_e32 v85, v78
	v_sin_f32_e32 v78, v78
	v_cos_f32_e32 v82, v79
	v_sin_f32_e32 v79, v79
	v_cos_f32_e32 v83, v80
	v_sin_f32_e32 v80, v80
	v_mul_f32_e32 v70, v74, v70
	v_mul_f32_e32 v71, v75, v71
	v_mul_f32_e32 v72, v76, v72
	v_mul_f32_e32 v73, v77, v73
	ds_bpermute_b32 v76, v90, v71
	ds_bpermute_b32 v77, v90, v70
	ds_bpermute_b32 v74, v90, v73
	ds_bpermute_b32 v75, v90, v72
	s_waitcnt lgkmcnt(3)
; __device__ __forceinline__ unsigned pk2(float lo, float hi) { unsigned r; asm volatile("v_cvt_pk_bf16_f32 %0, %1, %2" : "=v"(r) : "v"(lo), "v"(hi)); return r; }
; __device__ __forceinline__ void rope16(float (&v)[4], int kq, float pos, bool on) {
; #pragma unroll
;     for (int r = 0; r < 4; ++r) {
;         const int j = (4 * kq + r) & 7;
;         const float ang = pos * exp2f(-(float)j * (13.287712379549449f / 8.f)), cs = __cosf(ang), sn = __sinf(ang);
;         const float other = __shfl_xor(v[r], 32);
;         const float rot = kq < 2 ? v[r] * cs - other * sn : other * sn + v[r] * cs;
;         v[r] = on ? rot : v[r];
;     }
; }
; __device__ __forceinline__ void ph_prep(bf16_t* Z, const bf16_t* WUQ, const bf16_t* WUKV, const bf16_t* D64, const float* qkq, const float* qkk,
;                                         bf16_t* Q, bf16_t* Kb, bf16_t* Vb, bf16_t* F1lat, bf16_t* F1ctx, unsigned char* lds_) { PH_IDS;
;     ...
;                 const int row = rowc[tt]; const bool lat = row < RL; const int b = row_batch(row), t = lat ? (row & 2047) : ((row - RL) & 255), qi = lat ? t : 2048 + t;
;                 bf16_t* qo = Q + ((size_t)(b * 4 + h) * 2304 + qi) * 96 + 4 * kq;
; #pragma unroll
;                 for (int nt = 0; nt < 6; ++nt) {
;                     const f32x4 w = *(const f32x4*)(qkq + 16 * nt + 4 * kq);
;                     float v[4];
; #pragma unroll
;                     for (int r = 0; r < 4; ++r) v[r] = acc[nt][tt][r] * fac * w[r];
;                     if (nt >= 4) rope16(v, kq, nt == 4 ? (float)(t >> 6) : (float)(t & 63), lat);
;                     fa::u32x2 o; o.x = fa::pk2(v[0], v[1]); o.y = fa::pk2(v[2], v[3]);
;                     if (valid[tt]) *(fa::u32x2*)(qo + 16 * nt) = o;
;                 }
	v_mul_f32_e32 v76, v81, v76
	s_waitcnt lgkmcnt(2)
	v_mul_f32_e32 v77, v78, v77
	s_waitcnt lgkmcnt(1)
	v_mul_f32_e32 v74, v79, v74
	s_waitcnt lgkmcnt(0)
	v_mul_f32_e32 v75, v80, v75
	v_cndmask_b32_e64 v76, v76, -v76, s[4:5]
	v_cndmask_b32_e64 v77, v77, -v77, s[4:5]
	v_cndmask_b32_e64 v74, v74, -v74, s[4:5]
	v_cndmask_b32_e64 v75, v75, -v75, s[4:5]
	v_fmac_f32_e32 v76, v84, v71
	v_fmac_f32_e32 v77, v85, v70
	v_fmac_f32_e32 v74, v82, v73
	v_fmac_f32_e32 v75, v83, v72
	v_cndmask_b32_e32 v71, v71, v76, vcc
	v_cndmask_b32_e32 v70, v70, v77, vcc
	v_cndmask_b32_e32 v73, v73, v74, vcc
	v_cndmask_b32_e32 v72, v72, v75, vcc
	v_cvt_pk_bf16_f32 v70, v70, v71
	v_cvt_pk_bf16_f32 v71, v72, v73
	global_store_dwordx2 v[96:97], v[70:71], off offset:128
	v_mov_b64_e32 v[70:71], v[244:245]
	v_mov_b64_e32 v[72:73], v[246:247]
	v_mul_f32_e32 v76, v165, v191
	v_mul_f32_e32 v77, v164, v191
	v_mul_f32_e32 v74, v167, v191
	v_mul_f32_e32 v75, v166, v191
	v_mul_f32_e32 v76, 0.15915494, v76
	v_mul_f32_e32 v77, 0.15915494, v77
	v_mul_f32_e32 v74, 0.15915494, v74
	v_mul_f32_e32 v75, 0.15915494, v75
	v_cos_f32_e32 v80, v76
	v_sin_f32_e32 v76, v76
	v_cos_f32_e32 v81, v77
	v_sin_f32_e32 v77, v77
	v_cos_f32_e32 v78, v74
	v_sin_f32_e32 v74, v74
	v_cos_f32_e32 v79, v75
	v_sin_f32_e32 v75, v75
	ds_bpermute_b32 v82, v91, v95
	v_mul_f32_e32 v66, v66, v70
	v_mul_f32_e32 v67, v67, v71
	v_mul_f32_e32 v68, v68, v72
	v_mul_f32_e32 v69, v69, v73
	ds_bpermute_b32 v72, v90, v67
	ds_bpermute_b32 v73, v90, v66
	ds_bpermute_b32 v70, v90, v69
	ds_bpermute_b32 v71, v90, v68
	s_waitcnt lgkmcnt(3)
	v_mul_f32_e32 v72, v76, v72
	s_waitcnt lgkmcnt(2)
	v_mul_f32_e32 v73, v77, v73
	s_waitcnt lgkmcnt(1)
	v_mul_f32_e32 v70, v74, v70
	s_waitcnt lgkmcnt(0)
	v_mul_f32_e32 v71, v75, v71
	v_cndmask_b32_e64 v72, v72, -v72, s[4:5]
	v_cndmask_b32_e64 v73, v73, -v73, s[4:5]
	v_cndmask_b32_e64 v70, v70, -v70, s[4:5]
	v_cndmask_b32_e64 v71, v71, -v71, s[4:5]
	v_fmac_f32_e32 v72, v80, v67
	v_fmac_f32_e32 v73, v81, v66
	v_fmac_f32_e32 v70, v78, v69
	v_fmac_f32_e32 v71, v79, v68
	v_cndmask_b32_e32 v67, v67, v72, vcc
	v_cndmask_b32_e32 v66, v66, v73, vcc
	v_cndmask_b32_e32 v69, v69, v70, vcc
	v_cndmask_b32_e32 v68, v68, v71, vcc
	v_cvt_pk_bf16_f32 v66, v66, v67
	v_cvt_pk_bf16_f32 v67, v68, v69
	global_store_dwordx2 v[96:97], v[66:67], off offset:160
	v_mov_b64_e32 v[70:71], v[224:225]
	v_mov_b64_e32 v[72:73], v[226:227]
	v_mul_f32_e32 v68, v63, v63
	v_fmac_f32_e32 v68, v62, v62
	v_fmac_f32_e32 v68, v64, v64
	v_fmac_f32_e32 v68, v65, v65
	v_fmac_f32_e32 v68, v58, v58
	v_fmac_f32_e32 v68, v59, v59
	v_fmac_f32_e32 v68, v60, v60
	v_fmac_f32_e32 v68, v61, v61
	v_fmac_f32_e32 v68, v54, v54
	v_fmac_f32_e32 v68, v55, v55
	v_fmac_f32_e32 v68, v56, v56
	v_fmac_f32_e32 v68, v57, v57
	v_fmac_f32_e32 v68, v46, v46
	v_fmac_f32_e32 v68, v47, v47
	v_fmac_f32_e32 v68, v48, v48
	v_pk_mul_f32 v[74:75], v[50:51], v[50:51]
	v_cmp_gt_i32_e32 vcc, s50, v188
	v_fmac_f32_e32 v68, v49, v49
	v_add_f32_e32 v68, v74, v68
	v_cndmask_b32_e32 v69, v190, v189, vcc
	v_cndmask_b32_e32 v80, v177, v178, vcc
	v_pk_mul_f32 v[66:67], v[52:53], v[52:53]
	v_lshl_add_u32 v81, v69, 2, s29
	v_and_b32_e32 v69, v80, v188
	v_add_f32_e32 v68, v75, v68
	v_or_b32_e32 v80, 0x800, v69
	v_add_f32_e32 v66, v66, v68
	v_pk_mul_f32 v[78:79], v[42:43], v[42:43]
	v_cndmask_b32_e32 v100, v80, v69, vcc
	v_add_f32_e32 v80, v95, v82
	v_add_f32_e32 v66, v67, v66
	ds_bpermute_b32 v82, v90, v80
	v_add_f32_e32 v66, v78, v66
	v_pk_mul_f32 v[76:77], v[44:45], v[44:45]
	v_add_f32_e32 v66, v79, v66
	v_add_f32_e32 v66, v76, v66
	v_add_f32_e32 v66, v77, v66
	ds_bpermute_b32 v67, v91, v66
	s_waitcnt lgkmcnt(1)
	v_add_f32_e32 v80, v80, v82
	v_fmamk_f32 v80, v80, 0x3b800000, v175
	v_mul_f32_e32 v68, 0x4b800000, v80
	v_cmp_gt_f32_e64 s[12:13], s53, v80
	s_waitcnt lgkmcnt(0)
	v_add_f32_e32 v66, v66, v67
	ds_bpermute_b32 v67, v90, v66
	v_cndmask_b32_e64 v68, v80, v68, s[12:13]
	v_rsq_f32_e32 v68, v68
	v_mad_i64_i32 v[74:75], s[14:15], v81, s51, v[100:101]
	s_waitcnt lgkmcnt(0)
	v_add_f32_e32 v66, v66, v67
	v_mul_f32_e32 v76, 0x45800000, v68
	v_cndmask_b32_e64 v68, v68, v76, s[12:13]
	v_mul_f32_e32 v76, v68, v68
	v_mul_f32_e32 v66, v66, v76
	v_fmamk_f32 v66, v66, 0x3c2aaaab, v175
	v_mul_f32_e32 v67, 0x4b800000, v66
	v_cmp_gt_f32_e64 s[12:13], s53, v66
	s_nop 1
	v_cndmask_b32_e64 v66, v66, v67, s[12:13]
	v_rsq_f32_e32 v76, v66
	v_mad_u64_u32 v[66:67], s[14:15], v74, s52, v[110:111]
	v_mad_i32_i24 v67, v75, s52, v67
	v_mul_f32_e32 v74, 0x45800000, v76
	v_cndmask_b32_e64 v74, v76, v74, s[12:13]
	v_mul_f32_e32 v68, v68, v74
	v_mul_f32_e32 v68, 0x3e16c7fd, v68
	v_mul_f32_e32 v62, v62, v68
	v_mul_f32_e32 v63, v63, v68
	v_mul_f32_e32 v64, v64, v68
	v_mul_f32_e32 v65, v65, v68
	v_mul_f32_e32 v62, v70, v62
	v_mul_f32_e32 v63, v71, v63
	v_mul_f32_e32 v64, v72, v64
	v_mul_f32_e32 v65, v73, v65
	v_cvt_pk_bf16_f32 v62, v62, v63
	v_cvt_pk_bf16_f32 v63, v64, v65
	s_and_saveexec_b64 s[12:13], s[10:11]
	s_cbranch_execz .LBB0_576
	global_store_dwordx2 v[66:67], v[62:63], off

; __device__ __forceinline__ float bf2f(bf16_t v) { return __uint_as_float(((unsigned)v) << 16); }
; #define LAS __attribute__((address_space(3)))
; __device__ __forceinline__ void ph_prep(bf16_t* Z, const bf16_t* WUQ, const bf16_t* WUKV, const bf16_t* D64, const float* qkq, const float* qkk,
;                                         bf16_t* Q, bf16_t* Kb, bf16_t* Vb, bf16_t* F1lat, bf16_t* F1ctx, unsigned char* lds_) { PH_IDS;
;     ...
;             for (int pass = 0; pass < 2; ++pass) {
;                 f32x4 acc[4][3];
; #pragma unroll
;                 for (int tt = 0; tt < 3; ++tt)
; #pragma unroll
;                     for (int nt = 0; nt < 4; ++nt) acc[nt][tt] = (f32x4){0.f, 0.f, 0.f, 0.f};
; #pragma unroll
;                 for (int ks = 0; ks < 4; ++ks) {
;                     bf16x8 bq[3], aw[4];
; #pragma unroll
;                     for (int tt = 0; tt < 3; ++tt) { bq[tt] = *(const LAS bf16x8*)(sm + O_KV + rl[tt] * P_KV + (32 * ks + 8 * kq) * 2);
;                         if (pass == 0) {
; #pragma unroll
;                             for (int e = 0; e < 8; ++e) { const float f = bf2f((bf16_t)bq[tt][e]); ssq[tt] += f * f; } } }
; #pragma unroll
;                     for (int nt = 0; nt < 4; ++nt) aw[nt] = *(const bf16x8*)(WUKV + (size_t)(h * 128 + pass * 64 + 16 * nt + c16) * 128 + 32 * ks + 8 * kq);
; #pragma unroll
;                     for (int nt = 0; nt < 4; ++nt)
; #pragma unroll
;                         for (int tt = 0; tt < 3; ++tt) acc[nt][tt] = __builtin_amdgcn_mfma_f32_16x16x32_bf16(aw[nt], bq[tt], acc[nt][tt], 0, 0, 0);
;                 }
.LBB0_2337:
	v_or_b32_e32 v38, s61, v173
	v_ashrrev_i32_e32 v39, 31, v38
	v_lshlrev_b64 v[22:23], 8, v[38:39]
	v_lshl_add_u64 v[150:151], v[102:103], 0, v[22:23]
	v_or_b32_e32 v22, 16, v38
	v_or_b32_e32 v34, 32, v38
	v_or_b32_e32 v46, 48, v38
	v_ashrrev_i32_e32 v23, 31, v22
	v_ashrrev_i32_e32 v35, 31, v34
	v_ashrrev_i32_e32 v47, 31, v46
	v_lshlrev_b64 v[22:23], 8, v[22:23]
	v_lshlrev_b64 v[34:35], 8, v[34:35]
	v_lshlrev_b64 v[46:47], 8, v[46:47]
	v_lshl_add_u64 v[152:153], v[102:103], 0, v[22:23]
	v_lshl_add_u64 v[154:155], v[102:103], 0, v[34:35]
	v_lshl_add_u64 v[156:157], v[102:103], 0, v[46:47]
	global_load_dwordx4 v[30:33], v[150:151], off
	global_load_dwordx4 v[42:45], v[152:153], off
	global_load_dwordx4 v[54:57], v[154:155], off
	global_load_dwordx4 v[70:73], v[156:157], off
	global_load_dwordx4 v[78:81], v[150:151], off offset:64
	global_load_dwordx4 v[82:85], v[152:153], off offset:64
	global_load_dwordx4 v[110:113], v[154:155], off offset:64
	global_load_dwordx4 v[134:137], v[156:157], off offset:64
	ds_read_b128 v[66:69], v86 offset:64
	s_and_b64 vcc, exec, s[18:19]
	s_waitcnt vmcnt(7) lgkmcnt(3)
	v_mfma_f32_16x16x32_bf16 v[22:25], v[30:33], v[18:21], 0
	s_waitcnt lgkmcnt(2)
	v_mfma_f32_16x16x32_bf16 v[26:29], v[30:33], v[58:61], 0
	s_waitcnt lgkmcnt(1)
	v_mfma_f32_16x16x32_bf16 v[30:33], v[30:33], v[62:65], 0
	s_waitcnt vmcnt(6)
	v_mfma_f32_16x16x32_bf16 v[34:37], v[42:45], v[18:21], 0
	v_mfma_f32_16x16x32_bf16 v[38:41], v[42:45], v[58:61], 0
	v_mfma_f32_16x16x32_bf16 v[42:45], v[42:45], v[62:65], 0
	s_waitcnt vmcnt(5)
	v_mfma_f32_16x16x32_bf16 v[46:49], v[54:57], v[18:21], 0
	v_mfma_f32_16x16x32_bf16 v[50:53], v[54:57], v[58:61], 0
	v_mfma_f32_16x16x32_bf16 v[54:57], v[54:57], v[62:65], 0
	s_waitcnt vmcnt(4)
	v_mfma_f32_16x16x32_bf16 v[18:21], v[70:73], v[18:21], 0
	v_mfma_f32_16x16x32_bf16 v[58:61], v[70:73], v[58:61], 0
	v_mfma_f32_16x16x32_bf16 v[62:65], v[70:73], v[62:65], 0
	s_cbranch_vccnz .LBB0_2378
	s_waitcnt lgkmcnt(0)
	v_and_b32_e32 v71, 0xffff0000, v66
	v_lshlrev_b32_e32 v70, 16, v66
	v_pk_mul_f32 v[70:71], v[70:71], v[70:71]
	s_nop 0
	v_add_f32_e32 v70, v252, v70
	v_add_f32_e32 v72, v71, v70
	v_and_b32_e32 v71, 0xffff0000, v67
	v_lshlrev_b32_e32 v70, 16, v67
	v_pk_mul_f32 v[70:71], v[70:71], v[70:71]
	s_nop 0
	v_add_f32_e32 v70, v70, v72
	v_add_f32_e32 v72, v71, v70
	v_and_b32_e32 v71, 0xffff0000, v68
	v_lshlrev_b32_e32 v70, 16, v68
	v_pk_mul_f32 v[70:71], v[70:71], v[70:71]
	s_nop 0
	v_add_f32_e32 v70, v70, v72
	v_add_f32_e32 v72, v71, v70
	v_and_b32_e32 v71, 0xffff0000, v69
	v_lshlrev_b32_e32 v70, 16, v69
	v_pk_mul_f32 v[70:71], v[70:71], v[70:71]
	s_nop 0
	v_add_f32_e32 v70, v70, v72
	v_add_f32_e32 v252, v71, v70
	ds_read_b128 v[70:73], v94 offset:64
	s_and_b64 vcc, exec, s[18:19]
	s_cbranch_vccz .LBB0_2379

; __device__ __forceinline__ float bf2f(bf16_t v) { return __uint_as_float(((unsigned)v) << 16); }
; #define LAS __attribute__((address_space(3)))
; __device__ __forceinline__ void ph_prep(bf16_t* Z, const bf16_t* WUQ, const bf16_t* WUKV, const bf16_t* D64, const float* qkq, const float* qkk,
;                                         bf16_t* Q, bf16_t* Kb, bf16_t* Vb, bf16_t* F1lat, bf16_t* F1ctx, unsigned char* lds_) { PH_IDS;
;     ...
;                 for (int ks = 0; ks < 4; ++ks) {
;                     bf16x8 bq[3], aw[4];
; #pragma unroll
;                     for (int tt = 0; tt < 3; ++tt) { bq[tt] = *(const LAS bf16x8*)(sm + O_KV + rl[tt] * P_KV + (32 * ks + 8 * kq) * 2);
;                         if (pass == 0) {
; #pragma unroll
;                             for (int e = 0; e < 8; ++e) { const float f = bf2f((bf16_t)bq[tt][e]); ssq[tt] += f * f; } } }
; #pragma unroll
;                     for (int nt = 0; nt < 4; ++nt) aw[nt] = *(const bf16x8*)(WUKV + (size_t)(h * 128 + pass * 64 + 16 * nt + c16) * 128 + 32 * ks + 8 * kq);
; #pragma unroll
;                     for (int nt = 0; nt < 4; ++nt)
; #pragma unroll
;                         for (int tt = 0; tt < 3; ++tt) acc[nt][tt] = __builtin_amdgcn_mfma_f32_16x16x32_bf16(aw[nt], bq[tt], acc[nt][tt], 0, 0, 0);
;                 }
.LBB0_2340:
	s_waitcnt lgkmcnt(0)
	v_and_b32_e32 v125, 0xffff0000, v74
	v_lshlrev_b32_e32 v124, 16, v74
	v_pk_mul_f32 v[124:125], v[124:125], v[124:125]
	s_nop 0
	v_add_f32_e32 v124, v250, v124
	v_add_f32_e32 v98, v125, v124
	v_and_b32_e32 v125, 0xffff0000, v75
	v_lshlrev_b32_e32 v124, 16, v75
	v_pk_mul_f32 v[124:125], v[124:125], v[124:125]
	s_nop 0
	v_add_f32_e32 v124, v124, v98
	v_add_f32_e32 v98, v125, v124
	v_and_b32_e32 v125, 0xffff0000, v76
	v_lshlrev_b32_e32 v124, 16, v76
	v_pk_mul_f32 v[124:125], v[124:125], v[124:125]
	s_nop 0
	v_add_f32_e32 v124, v124, v98
	v_add_f32_e32 v98, v125, v124
	v_and_b32_e32 v125, 0xffff0000, v77
	v_lshlrev_b32_e32 v124, 16, v77
	v_pk_mul_f32 v[124:125], v[124:125], v[124:125]
	s_nop 0
	v_add_f32_e32 v124, v124, v98
	v_add_f32_e32 v250, v125, v124
.LBB0_2341:
	s_and_b64 vcc, exec, s[18:19]
	s_waitcnt vmcnt(3) lgkmcnt(2)
	v_mfma_f32_16x16x32_bf16 v[22:25], v[78:81], v[66:69], v[22:25]
	s_waitcnt lgkmcnt(1)
	v_mfma_f32_16x16x32_bf16 v[26:29], v[78:81], v[70:73], v[26:29]
	s_waitcnt lgkmcnt(0)
	v_mfma_f32_16x16x32_bf16 v[30:33], v[78:81], v[74:77], v[30:33]
	s_waitcnt vmcnt(2)
	v_mfma_f32_16x16x32_bf16 v[34:37], v[82:85], v[66:69], v[34:37]
	v_mfma_f32_16x16x32_bf16 v[38:41], v[82:85], v[70:73], v[38:41]
	v_mfma_f32_16x16x32_bf16 v[42:45], v[82:85], v[74:77], v[42:45]
	s_waitcnt vmcnt(1)
	v_mfma_f32_16x16x32_bf16 v[46:49], v[110:113], v[66:69], v[46:49]
	v_mfma_f32_16x16x32_bf16 v[50:53], v[110:113], v[70:73], v[50:53]
	v_mfma_f32_16x16x32_bf16 v[54:57], v[110:113], v[74:77], v[54:57]
	ds_read_b128 v[78:81], v86 offset:128
	s_waitcnt vmcnt(0)
	v_mfma_f32_16x16x32_bf16 v[18:21], v[134:137], v[66:69], v[18:21]
	v_mfma_f32_16x16x32_bf16 v[58:61], v[134:137], v[70:73], v[58:61]
	v_mfma_f32_16x16x32_bf16 v[62:65], v[134:137], v[74:77], v[62:65]
	global_load_dwordx4 v[66:69], v[150:151], off offset:128
	global_load_dwordx4 v[70:73], v[152:153], off offset:128
	global_load_dwordx4 v[74:77], v[154:155], off offset:128
	global_load_dwordx4 v[110:113], v[156:157], off offset:128
	global_load_dwordx4 v[134:137], v[154:155], off offset:192
	s_cbranch_vccnz .LBB0_2380
	s_waitcnt lgkmcnt(0)
	v_and_b32_e32 v125, 0xffff0000, v78
	v_lshlrev_b32_e32 v124, 16, v78
	v_pk_mul_f32 v[124:125], v[124:125], v[124:125]
	s_nop 0
	v_add_f32_e32 v124, v252, v124
	v_add_f32_e32 v98, v125, v124
	v_and_b32_e32 v125, 0xffff0000, v79
	v_lshlrev_b32_e32 v124, 16, v79
	v_pk_mul_f32 v[124:125], v[124:125], v[124:125]
	s_nop 0
	v_add_f32_e32 v124, v124, v98
	v_add_f32_e32 v98, v125, v124
	v_and_b32_e32 v125, 0xffff0000, v80
	v_lshlrev_b32_e32 v124, 16, v80
	v_pk_mul_f32 v[124:125], v[124:125], v[124:125]
	s_nop 0
	v_add_f32_e32 v124, v124, v98
	v_add_f32_e32 v98, v125, v124
	v_and_b32_e32 v125, 0xffff0000, v81
	v_lshlrev_b32_e32 v124, 16, v81
	v_pk_mul_f32 v[124:125], v[124:125], v[124:125]
	s_nop 0
	v_add_f32_e32 v124, v124, v98
	v_add_f32_e32 v252, v125, v124
	ds_read_b128 v[82:85], v94 offset:128
	s_and_b64 vcc, exec, s[18:19]
	s_cbranch_vccz .LBB0_2381

; __device__ __forceinline__ float bf2f(bf16_t v) { return __uint_as_float(((unsigned)v) << 16); }
; #define LAS __attribute__((address_space(3)))
; __device__ __forceinline__ void ph_prep(bf16_t* Z, const bf16_t* WUQ, const bf16_t* WUKV, const bf16_t* D64, const float* qkq, const float* qkk,
;                                         bf16_t* Q, bf16_t* Kb, bf16_t* Vb, bf16_t* F1lat, bf16_t* F1ctx, unsigned char* lds_) { PH_IDS;
;     ...
;                 for (int ks = 0; ks < 4; ++ks) {
;                     bf16x8 bq[3], aw[4];
; #pragma unroll
;                     for (int tt = 0; tt < 3; ++tt) { bq[tt] = *(const LAS bf16x8*)(sm + O_KV + rl[tt] * P_KV + (32 * ks + 8 * kq) * 2);
;                         if (pass == 0) {
; #pragma unroll
;                             for (int e = 0; e < 8; ++e) { const float f = bf2f((bf16_t)bq[tt][e]); ssq[tt] += f * f; } } }
; #pragma unroll
;                     for (int nt = 0; nt < 4; ++nt) aw[nt] = *(const bf16x8*)(WUKV + (size_t)(h * 128 + pass * 64 + 16 * nt + c16) * 128 + 32 * ks + 8 * kq);
; #pragma unroll
;                     for (int nt = 0; nt < 4; ++nt)
; #pragma unroll
;                         for (int tt = 0; tt < 3; ++tt) acc[nt][tt] = __builtin_amdgcn_mfma_f32_16x16x32_bf16(aw[nt], bq[tt], acc[nt][tt], 0, 0, 0);
;                 }
.LBB0_2344:
	s_waitcnt lgkmcnt(0)
	v_and_b32_e32 v125, 0xffff0000, v90
	v_lshlrev_b32_e32 v124, 16, v90
	v_pk_mul_f32 v[124:125], v[124:125], v[124:125]
	s_nop 0
	v_add_f32_e32 v124, v250, v124
	v_add_f32_e32 v98, v125, v124
	v_and_b32_e32 v125, 0xffff0000, v91
	v_lshlrev_b32_e32 v124, 16, v91
	v_pk_mul_f32 v[124:125], v[124:125], v[124:125]
	s_nop 0
	v_add_f32_e32 v124, v124, v98
	v_add_f32_e32 v98, v125, v124
	v_and_b32_e32 v125, 0xffff0000, v92
	v_lshlrev_b32_e32 v124, 16, v92
	v_pk_mul_f32 v[124:125], v[124:125], v[124:125]
	s_nop 0
	v_add_f32_e32 v124, v124, v98
	v_add_f32_e32 v98, v125, v124
	v_and_b32_e32 v125, 0xffff0000, v93
	v_lshlrev_b32_e32 v124, 16, v93
	v_pk_mul_f32 v[124:125], v[124:125], v[124:125]
	s_nop 0
	v_add_f32_e32 v124, v124, v98
	v_add_f32_e32 v250, v125, v124
.LBB0_2345:
	ds_read_b128 v[86:89], v86 offset:192
	s_and_b64 vcc, exec, s[18:19]
	s_waitcnt vmcnt(4) lgkmcnt(3)
	v_mfma_f32_16x16x32_bf16 v[22:25], v[66:69], v[78:81], v[22:25]
	s_waitcnt lgkmcnt(2)
	v_mfma_f32_16x16x32_bf16 v[26:29], v[66:69], v[82:85], v[26:29]
	s_waitcnt lgkmcnt(1)
	v_mfma_f32_16x16x32_bf16 v[30:33], v[66:69], v[90:93], v[30:33]
	s_waitcnt vmcnt(3)
	v_mfma_f32_16x16x32_bf16 v[66:69], v[70:73], v[90:93], v[42:45]
	s_nop 2
	v_mfma_f32_16x16x32_bf16 v[34:37], v[70:73], v[78:81], v[34:37]
	v_mfma_f32_16x16x32_bf16 v[38:41], v[70:73], v[82:85], v[38:41]
	s_waitcnt vmcnt(2)
	v_mfma_f32_16x16x32_bf16 v[70:73], v[74:77], v[78:81], v[46:49]
	v_mfma_f32_16x16x32_bf16 v[50:53], v[74:77], v[82:85], v[50:53]
	v_mfma_f32_16x16x32_bf16 v[74:77], v[74:77], v[90:93], v[54:57]
	s_waitcnt vmcnt(1)
	v_mfma_f32_16x16x32_bf16 v[18:21], v[110:113], v[78:81], v[18:21]
	v_mfma_f32_16x16x32_bf16 v[78:81], v[110:113], v[82:85], v[58:61]
	v_mfma_f32_16x16x32_bf16 v[82:85], v[110:113], v[90:93], v[62:65]
	global_load_dwordx4 v[42:45], v[150:151], off offset:192
	global_load_dwordx4 v[54:57], v[152:153], off offset:192
	global_load_dwordx4 v[110:113], v[156:157], off offset:192
	s_cbranch_vccnz .LBB0_2382
	s_waitcnt lgkmcnt(0)
	v_and_b32_e32 v125, 0xffff0000, v86
	v_lshlrev_b32_e32 v124, 16, v86
	v_pk_mul_f32 v[124:125], v[124:125], v[124:125]
	s_nop 0
	v_add_f32_e32 v124, v252, v124
	v_add_f32_e32 v98, v125, v124
	v_and_b32_e32 v125, 0xffff0000, v87
	v_lshlrev_b32_e32 v124, 16, v87
	v_pk_mul_f32 v[124:125], v[124:125], v[124:125]
	s_nop 0
	v_add_f32_e32 v124, v124, v98
	v_add_f32_e32 v98, v125, v124
	v_and_b32_e32 v125, 0xffff0000, v88
	v_lshlrev_b32_e32 v124, 16, v88
	v_pk_mul_f32 v[124:125], v[124:125], v[124:125]
	s_nop 0
	v_add_f32_e32 v124, v124, v98
	v_add_f32_e32 v98, v125, v124
	v_and_b32_e32 v125, 0xffff0000, v89
	v_lshlrev_b32_e32 v124, 16, v89
	v_pk_mul_f32 v[124:125], v[124:125], v[124:125]
	s_nop 0
	v_add_f32_e32 v124, v124, v98
	v_add_f32_e32 v252, v125, v124
	ds_read_b128 v[90:93], v94 offset:192
	s_and_b64 vcc, exec, s[18:19]
	s_cbranch_vccz .LBB0_2383

; __device__ __forceinline__ float bf2f(bf16_t v) { return __uint_as_float(((unsigned)v) << 16); }
; #define LAS __attribute__((address_space(3)))
; __device__ __forceinline__ unsigned pk2(float lo, float hi) { unsigned r; asm volatile("v_cvt_pk_bf16_f32 %0, %1, %2" : "=v"(r) : "v"(lo), "v"(hi)); return r; }
; __device__ __forceinline__ void ph_prep(bf16_t* Z, const bf16_t* WUQ, const bf16_t* WUKV, const bf16_t* D64, const float* qkq, const float* qkk,
;                                         bf16_t* Q, bf16_t* Kb, bf16_t* Vb, bf16_t* F1lat, bf16_t* F1ctx, unsigned char* lds_) { PH_IDS;
;     ...
;                 for (int ks = 0; ks < 4; ++ks) {
;                     bf16x8 bq[3], aw[4];
; #pragma unroll
;                     for (int tt = 0; tt < 3; ++tt) { bq[tt] = *(const LAS bf16x8*)(sm + O_KV + rl[tt] * P_KV + (32 * ks + 8 * kq) * 2);
;                         if (pass == 0) {
; #pragma unroll
;                             for (int e = 0; e < 8; ++e) { const float f = bf2f((bf16_t)bq[tt][e]); ssq[tt] += f * f; } } }
; #pragma unroll
;                     for (int nt = 0; nt < 4; ++nt) aw[nt] = *(const bf16x8*)(WUKV + (size_t)(h * 128 + pass * 64 + 16 * nt + c16) * 128 + 32 * ks + 8 * kq);
; #pragma unroll
;                     for (int nt = 0; nt < 4; ++nt)
; #pragma unroll
;                         for (int tt = 0; tt < 3; ++tt) acc[nt][tt] = __builtin_amdgcn_mfma_f32_16x16x32_bf16(aw[nt], bq[tt], acc[nt][tt], 0, 0, 0);
;                 }
;     ...
;                         bf16_t* vo = Vb + ((size_t)(b * 4 + h) * 2304 + ki) * 64 + 4 * kq;
; #pragma unroll
;                         for (int nt = 0; nt < 4; ++nt) { fa::u32x2 o; o.x = fa::pk2(acc[nt][tt][0] * rstd[tt], acc[nt][tt][1] * rstd[tt]); o.y = fa::pk2(acc[nt][tt][2] * rstd[tt], acc[nt][tt][3] * rstd[tt]);
;                             if (valid[tt]) *(fa::u32x2*)(vo + 16 * nt) = o; }
.LBB0_2348:
	s_waitcnt lgkmcnt(0)
	v_and_b32_e32 v125, 0xffff0000, v94
	v_lshlrev_b32_e32 v124, 16, v94
	v_pk_mul_f32 v[124:125], v[124:125], v[124:125]
	s_nop 0
	v_add_f32_e32 v124, v250, v124
	v_add_f32_e32 v98, v125, v124
	v_and_b32_e32 v125, 0xffff0000, v95
	v_lshlrev_b32_e32 v124, 16, v95
	v_pk_mul_f32 v[124:125], v[124:125], v[124:125]
	s_nop 0
	v_add_f32_e32 v124, v124, v98
	v_add_f32_e32 v98, v125, v124
	v_and_b32_e32 v125, 0xffff0000, v96
	v_lshlrev_b32_e32 v124, 16, v96
	v_pk_mul_f32 v[124:125], v[124:125], v[124:125]
	s_nop 0
	v_add_f32_e32 v124, v124, v98
	v_add_f32_e32 v98, v125, v124
	v_and_b32_e32 v125, 0xffff0000, v97
	v_lshlrev_b32_e32 v124, 16, v97
	v_pk_mul_f32 v[124:125], v[124:125], v[124:125]
	s_nop 0
	v_add_f32_e32 v124, v124, v98
	v_add_f32_e32 v250, v125, v124
.LBB0_2349:
	s_mov_b64 s[18:19], -1
	s_and_b64 vcc, exec, s[34:35]
	s_waitcnt vmcnt(2) lgkmcnt(2)
	v_mfma_f32_16x16x32_bf16 v[62:65], v[42:45], v[86:89], v[22:25]
	s_nop 2
	s_waitcnt lgkmcnt(1)
	v_mfma_f32_16x16x32_bf16 v[46:49], v[42:45], v[90:93], v[26:29]
	s_waitcnt vmcnt(1) lgkmcnt(0)
	v_mfma_f32_16x16x32_bf16 v[26:29], v[54:57], v[94:97], v[66:69]
	s_nop 2
	v_mfma_f32_16x16x32_bf16 v[30:33], v[42:45], v[94:97], v[30:33]
	v_mfma_f32_16x16x32_bf16 v[58:61], v[54:57], v[86:89], v[34:37]
	v_mfma_f32_16x16x32_bf16 v[42:45], v[54:57], v[90:93], v[38:41]
	v_mfma_f32_16x16x32_bf16 v[54:57], v[134:137], v[86:89], v[70:73]
	v_mfma_f32_16x16x32_bf16 v[38:41], v[134:137], v[90:93], v[50:53]
	v_mfma_f32_16x16x32_bf16 v[22:25], v[134:137], v[94:97], v[74:77]
	s_waitcnt vmcnt(0)
	v_mfma_f32_16x16x32_bf16 v[50:53], v[110:113], v[86:89], v[18:21]
	v_mfma_f32_16x16x32_bf16 v[34:37], v[110:113], v[90:93], v[78:81]
	v_mfma_f32_16x16x32_bf16 v[18:21], v[110:113], v[94:97], v[82:85]
	s_cbranch_vccz .LBB0_2351
	v_mul_f32_e32 v66, v194, v62
	v_mul_f32_e32 v67, v194, v63
	v_cvt_pk_bf16_f32 v66, v66, v67
	v_mul_f32_e32 v67, v194, v64
	v_mul_f32_e32 v68, v194, v65
	v_cvt_pk_bf16_f32 v67, v67, v68
	global_store_dwordx2 v[138:139], v[66:67], off
	v_mul_f32_e32 v66, v194, v58
	v_mul_f32_e32 v67, v194, v59
	v_cvt_pk_bf16_f32 v66, v66, v67
	v_mul_f32_e32 v67, v194, v60
	v_mul_f32_e32 v68, v194, v61
	v_cvt_pk_bf16_f32 v67, v67, v68
	global_store_dwordx2 v[138:139], v[66:67], off offset:32
	v_mul_f32_e32 v66, v194, v54
	v_mul_f32_e32 v67, v194, v55
	v_cvt_pk_bf16_f32 v66, v66, v67
	v_mul_f32_e32 v67, v194, v56
	v_mul_f32_e32 v68, v194, v57
	v_cvt_pk_bf16_f32 v67, v67, v68
	global_store_dwordx2 v[138:139], v[66:67], off offset:64
	v_mul_f32_e32 v66, v194, v50
	v_mul_f32_e32 v67, v194, v51
	v_cvt_pk_bf16_f32 v66, v66, v67
	v_mul_f32_e32 v67, v194, v52
	v_mul_f32_e32 v68, v194, v53
	v_cvt_pk_bf16_f32 v67, v67, v68
	global_store_dwordx2 v[138:139], v[66:67], off offset:96
	s_mov_b64 s[18:19], 0

; __device__ __forceinline__ float bf2f(bf16_t v) { return __uint_as_float(((unsigned)v) << 16); }
; #define LAS __attribute__((address_space(3)))
; __device__ __forceinline__ void ph_prep(bf16_t* Z, const bf16_t* WUQ, const bf16_t* WUKV, const bf16_t* D64, const float* qkq, const float* qkk,
;                                         bf16_t* Q, bf16_t* Kb, bf16_t* Vb, bf16_t* F1lat, bf16_t* F1ctx, unsigned char* lds_) { PH_IDS;
;     ...
; #pragma unroll
;                     for (int tt = 0; tt < 3; ++tt) { bq[tt] = *(const LAS bf16x8*)(sm + O_KV + rl[tt] * P_KV + (32 * ks + 8 * kq) * 2);
;                         if (pass == 0) {
; #pragma unroll
;                             for (int e = 0; e < 8; ++e) { const float f = bf2f((bf16_t)bq[tt][e]); ssq[tt] += f * f; } } }
.LBB0_2381:
	s_waitcnt lgkmcnt(0)
	v_and_b32_e32 v125, 0xffff0000, v82
	v_lshlrev_b32_e32 v124, 16, v82
	v_pk_mul_f32 v[124:125], v[124:125], v[124:125]
	s_nop 0
	v_add_f32_e32 v124, v251, v124
	v_add_f32_e32 v98, v125, v124
	v_and_b32_e32 v125, 0xffff0000, v83
	v_lshlrev_b32_e32 v124, 16, v83
	v_pk_mul_f32 v[124:125], v[124:125], v[124:125]
	s_nop 0
	v_add_f32_e32 v124, v124, v98
	v_add_f32_e32 v98, v125, v124
	v_and_b32_e32 v125, 0xffff0000, v84
	v_lshlrev_b32_e32 v124, 16, v84
	v_pk_mul_f32 v[124:125], v[124:125], v[124:125]
	s_nop 0
	v_add_f32_e32 v124, v124, v98
	v_add_f32_e32 v98, v125, v124
	v_and_b32_e32 v125, 0xffff0000, v85
	v_lshlrev_b32_e32 v124, 16, v85
	v_pk_mul_f32 v[124:125], v[124:125], v[124:125]
	s_nop 0
	v_add_f32_e32 v124, v124, v98
	v_add_f32_e32 v251, v125, v124
	ds_read_b128 v[90:93], v95 offset:128
	s_and_b64 vcc, exec, s[18:19]
	s_cbranch_vccz .LBB0_2344
	s_branch .LBB0_2345

; __device__ __forceinline__ float bf2f(bf16_t v) { return __uint_as_float(((unsigned)v) << 16); }
; #define LAS __attribute__((address_space(3)))
; __device__ __forceinline__ void ph_prep(bf16_t* Z, const bf16_t* WUQ, const bf16_t* WUKV, const bf16_t* D64, const float* qkq, const float* qkk,
;                                         bf16_t* Q, bf16_t* Kb, bf16_t* Vb, bf16_t* F1lat, bf16_t* F1ctx, unsigned char* lds_) { PH_IDS;
;     ...
; #pragma unroll
;                     for (int tt = 0; tt < 3; ++tt) { bq[tt] = *(const LAS bf16x8*)(sm + O_KV + rl[tt] * P_KV + (32 * ks + 8 * kq) * 2);
;                         if (pass == 0) {
; #pragma unroll
;                             for (int e = 0; e < 8; ++e) { const float f = bf2f((bf16_t)bq[tt][e]); ssq[tt] += f * f; } } }
.LBB0_2383:
	s_waitcnt lgkmcnt(0)
	v_and_b32_e32 v125, 0xffff0000, v90
	v_lshlrev_b32_e32 v124, 16, v90
	v_pk_mul_f32 v[124:125], v[124:125], v[124:125]
	s_nop 0
	v_add_f32_e32 v124, v251, v124
	v_add_f32_e32 v98, v125, v124
	v_and_b32_e32 v125, 0xffff0000, v91
	v_lshlrev_b32_e32 v124, 16, v91
	v_pk_mul_f32 v[124:125], v[124:125], v[124:125]
	s_nop 0
	v_add_f32_e32 v124, v124, v98
	v_add_f32_e32 v98, v125, v124
	v_and_b32_e32 v125, 0xffff0000, v92
	v_lshlrev_b32_e32 v124, 16, v92
	v_pk_mul_f32 v[124:125], v[124:125], v[124:125]
	s_nop 0
	v_add_f32_e32 v124, v124, v98
	v_add_f32_e32 v98, v125, v124
	v_and_b32_e32 v125, 0xffff0000, v93
	v_lshlrev_b32_e32 v124, 16, v93
	v_pk_mul_f32 v[124:125], v[124:125], v[124:125]
	s_nop 0
	v_add_f32_e32 v124, v124, v98
	v_add_f32_e32 v251, v125, v124
	ds_read_b128 v[94:97], v95 offset:192
	s_and_b64 vcc, exec, s[18:19]
	s_cbranch_vccz .LBB0_2348
	s_branch .LBB0_2349

; __device__ __forceinline__ float bf2f(bf16_t v) { return __uint_as_float(((unsigned)v) << 16); }
; #define LAS __attribute__((address_space(3)))
; __device__ __forceinline__ void ph_prep(bf16_t* Z, const bf16_t* WUQ, const bf16_t* WUKV, const bf16_t* D64, const float* qkq, const float* qkk,
;                                         bf16_t* Q, bf16_t* Kb, bf16_t* Vb, bf16_t* F1lat, bf16_t* F1ctx, unsigned char* lds_) { PH_IDS;
;     ...
;             for (int ks = 0; ks < 8; ++ks) {
;                 bf16x8 bq[3], aw[6];
; #pragma unroll
;                 for (int tt = 0; tt < 3; ++tt) { bq[tt] = *(const LAS bf16x8*)(sm + O_QC + rl[tt] * P_QC + (32 * ks + 8 * kq) * 2);
; #pragma unroll
;                     for (int e = 0; e < 8; ++e) { const float f = bf2f((bf16_t)bq[tt][e]); ssq[tt] += f * f; } }
; #pragma unroll
;                 for (int nt = 0; nt < 6; ++nt) aw[nt] = *(const bf16x8*)(WUQ + (size_t)(h * 96 + 16 * nt + c16) * 256 + 32 * ks + 8 * kq);
; #pragma unroll
;                 for (int nt = 0; nt < 6; ++nt)
; #pragma unroll
;                     for (int tt = 0; tt < 3; ++tt) acc[nt][tt] = __builtin_amdgcn_mfma_f32_16x16x32_bf16(aw[nt], bq[tt], acc[nt][tt], 0, 0, 0);
;             }
.LBB0_2409:
	v_add_u32_e32 v220, v100, v141
	ds_read_b128 v[90:93], v220
	v_add_u32_e32 v221, v100, v142
	ds_read_b128 v[144:147], v221
	v_add_u32_e32 v222, v100, v140
	ds_read_b128 v[148:151], v222
	s_waitcnt lgkmcnt(2)
	v_lshlrev_b32_e32 v96, 16, v90
	v_fmac_f32_e32 v143, v96, v96
	v_and_b32_e32 v96, 0xffff0000, v90
	v_lshlrev_b32_e32 v97, 16, v91
	v_pk_mul_f32 v[96:97], v[96:97], v[96:97]
	v_lshl_add_u64 v[156:157], v[132:133], 0, s[12:13]
	v_add_f32_e32 v96, v96, v143
	v_add_f32_e32 v138, v97, v96
	v_and_b32_e32 v96, 0xffff0000, v91
	v_lshlrev_b32_e32 v97, 16, v92
	v_pk_mul_f32 v[96:97], v[96:97], v[96:97]
	v_lshl_add_u64 v[248:249], v[130:131], 0, s[12:13]
	v_add_f32_e32 v96, v96, v138
	v_add_f32_e32 v138, v97, v96
	v_and_b32_e32 v96, 0xffff0000, v92
	v_lshlrev_b32_e32 v97, 16, v93
	v_pk_mul_f32 v[96:97], v[96:97], v[96:97]
	v_lshl_add_u64 v[250:251], v[128:129], 0, s[12:13]
	v_add_f32_e32 v96, v96, v138
	v_add_f32_e32 v143, v97, v96
	v_and_b32_e32 v96, 0xffff0000, v93
	v_fmac_f32_e32 v143, v96, v96
	s_waitcnt lgkmcnt(1)
	v_lshlrev_b32_e32 v97, 16, v144
	s_waitcnt lgkmcnt(0)
	v_lshlrev_b32_e32 v96, 16, v148
	v_pk_fma_f32 v[94:95], v[96:97], v[96:97], v[94:95]
	v_and_b32_e32 v97, 0xffff0000, v144
	v_and_b32_e32 v96, 0xffff0000, v148
	v_pk_fma_f32 v[94:95], v[96:97], v[96:97], v[94:95]
	v_lshlrev_b32_e32 v97, 16, v145
	v_lshlrev_b32_e32 v96, 16, v149
	v_pk_fma_f32 v[94:95], v[96:97], v[96:97], v[94:95]
	v_and_b32_e32 v97, 0xffff0000, v145
	v_and_b32_e32 v96, 0xffff0000, v149
	v_pk_fma_f32 v[94:95], v[96:97], v[96:97], v[94:95]
	v_lshlrev_b32_e32 v97, 16, v146
	v_lshlrev_b32_e32 v96, 16, v150
	v_pk_fma_f32 v[94:95], v[96:97], v[96:97], v[94:95]
	v_and_b32_e32 v97, 0xffff0000, v146
	v_and_b32_e32 v96, 0xffff0000, v150
	v_pk_fma_f32 v[94:95], v[96:97], v[96:97], v[94:95]
	v_lshlrev_b32_e32 v97, 16, v147
	v_lshlrev_b32_e32 v96, 16, v151
	v_pk_fma_f32 v[94:95], v[96:97], v[96:97], v[94:95]
	v_and_b32_e32 v97, 0xffff0000, v147
	v_and_b32_e32 v96, 0xffff0000, v151
	v_pk_fma_f32 v[94:95], v[96:97], v[96:97], v[94:95]
	v_lshl_add_u64 v[96:97], v[136:137], 0, s[12:13]
	v_add_co_u32_e32 v96, vcc, s54, v96
	v_lshl_add_u64 v[138:139], v[134:135], 0, s[12:13]
	s_nop 0
	v_addc_co_u32_e32 v97, vcc, 0, v97, vcc
	v_add_co_u32_e32 v138, vcc, s54, v138
	v_lshl_add_u64 v[252:253], v[126:127], 0, s[12:13]
	s_nop 0
	v_addc_co_u32_e32 v139, vcc, 0, v139, vcc
	v_add_co_u32_e32 v156, vcc, s54, v156
	v_addc_co_u32_e32 v157, vcc, 0, v157, vcc
	v_add_co_u32_e32 v214, vcc, s54, v248
	s_nop 0
	v_addc_co_u32_e32 v215, vcc, 0, v249, vcc
	v_add_co_u32_e32 v216, vcc, s54, v250
	s_nop 0
	v_addc_co_u32_e32 v217, vcc, 0, v251, vcc
	v_add_co_u32_e32 v218, vcc, s54, v252
	s_nop 0
	v_addc_co_u32_e32 v219, vcc, 0, v253, vcc
	s_cmp_lg_u32 s12, 0
	s_cbranch_scc1 .Lqpf_a_L1
	global_load_dwordx4 v[152:155], v[96:97], off
	global_load_dwordx4 v[194:197], v[138:139], off
	global_load_dwordx4 v[198:201], v[156:157], off
	global_load_dwordx4 v[202:205], v[214:215], off
	global_load_dwordx4 v[206:209], v[216:217], off
	global_load_dwordx4 v[210:213], v[218:219], off
.Lqpf_a_L1:
	global_load_dwordx4 v[2:5], v[96:97], off offset:64
	global_load_dwordx4 v[6:9], v[138:139], off offset:64
	global_load_dwordx4 v[10:13], v[156:157], off offset:64
	global_load_dwordx4 v[14:17], v[214:215], off offset:64
	global_load_dwordx4 v[102:105], v[216:217], off offset:64
	global_load_dwordx4 v[106:109], v[218:219], off offset:64
	s_add_u32 s12, s12, 0x100
	s_addc_u32 s13, s13, 0
	v_add_u32_e32 v100, 0x100, v100
	s_cmpk_eq_i32 s12, 0x200
	s_waitcnt vmcnt(6)
	v_mfma_f32_16x16x32_bf16 v[86:89], v[152:155], v[90:93], v[86:89]
	v_mfma_f32_16x16x32_bf16 v[82:85], v[194:197], v[90:93], v[82:85]
	v_mfma_f32_16x16x32_bf16 v[78:81], v[198:201], v[90:93], v[78:81]
	v_mfma_f32_16x16x32_bf16 v[74:77], v[202:205], v[90:93], v[74:77]
	v_mfma_f32_16x16x32_bf16 v[70:73], v[206:209], v[90:93], v[70:73]
	v_mfma_f32_16x16x32_bf16 v[66:69], v[210:213], v[90:93], v[66:69]
	ds_read_b128 v[90:93], v220 offset:64
	v_mfma_f32_16x16x32_bf16 v[62:65], v[152:155], v[144:147], v[62:65]
	v_mfma_f32_16x16x32_bf16 v[58:61], v[194:197], v[144:147], v[58:61]
	v_mfma_f32_16x16x32_bf16 v[54:57], v[198:201], v[144:147], v[54:57]
	v_mfma_f32_16x16x32_bf16 v[46:49], v[202:205], v[144:147], v[46:49]
	v_mfma_f32_16x16x32_bf16 v[50:53], v[206:209], v[144:147], v[50:53]
	v_mfma_f32_16x16x32_bf16 v[42:45], v[210:213], v[144:147], v[42:45]
	s_waitcnt lgkmcnt(0)
	v_lshlrev_b32_e32 v144, 16, v90
	v_fmac_f32_e32 v143, v144, v144
	v_and_b32_e32 v144, 0xffff0000, v90
	v_lshlrev_b32_e32 v145, 16, v91
	v_pk_mul_f32 v[144:145], v[144:145], v[144:145]
	v_mfma_f32_16x16x32_bf16 v[38:41], v[152:155], v[148:151], v[38:41]
	v_add_f32_e32 v143, v144, v143
	v_add_f32_e32 v143, v145, v143
	v_and_b32_e32 v144, 0xffff0000, v91
	v_lshlrev_b32_e32 v145, 16, v92
	v_pk_mul_f32 v[144:145], v[144:145], v[144:145]
	v_mfma_f32_16x16x32_bf16 v[34:37], v[194:197], v[148:151], v[34:37]
	v_add_f32_e32 v143, v144, v143
	v_add_f32_e32 v143, v145, v143
	v_and_b32_e32 v144, 0xffff0000, v92
	v_lshlrev_b32_e32 v145, 16, v93
	v_pk_mul_f32 v[144:145], v[144:145], v[144:145]
	v_mfma_f32_16x16x32_bf16 v[30:33], v[198:201], v[148:151], v[30:33]
	v_add_f32_e32 v143, v144, v143
	v_add_f32_e32 v143, v145, v143
	v_and_b32_e32 v144, 0xffff0000, v93
	v_mfma_f32_16x16x32_bf16 v[22:25], v[202:205], v[148:151], v[22:25]
	v_fmac_f32_e32 v143, v144, v144
	v_mfma_f32_16x16x32_bf16 v[26:29], v[206:209], v[148:151], v[26:29]
	v_mfma_f32_16x16x32_bf16 v[18:21], v[210:213], v[148:151], v[18:21]
	ds_read_b128 v[144:147], v221 offset:64
	ds_read_b128 v[148:151], v222 offset:64
	s_waitcnt lgkmcnt(1)
; __device__ __forceinline__ float bf2f(bf16_t v) { return __uint_as_float(((unsigned)v) << 16); }
; #define LAS __attribute__((address_space(3)))
; __device__ __forceinline__ void ph_prep(bf16_t* Z, const bf16_t* WUQ, const bf16_t* WUKV, const bf16_t* D64, const float* qkq, const float* qkk,
;                                         bf16_t* Q, bf16_t* Kb, bf16_t* Vb, bf16_t* F1lat, bf16_t* F1ctx, unsigned char* lds_) { PH_IDS;
;     ...
; #pragma unroll 4
;             for (int ks = 0; ks < 8; ++ks) {
;                 bf16x8 bq[3], aw[6];
; #pragma unroll
;                 for (int tt = 0; tt < 3; ++tt) { bq[tt] = *(const LAS bf16x8*)(sm + O_QC + rl[tt] * P_QC + (32 * ks + 8 * kq) * 2);
; #pragma unroll
;                     for (int e = 0; e < 8; ++e) { const float f = bf2f((bf16_t)bq[tt][e]); ssq[tt] += f * f; } }
; #pragma unroll
;                 for (int nt = 0; nt < 6; ++nt) aw[nt] = *(const bf16x8*)(WUQ + (size_t)(h * 96 + 16 * nt + c16) * 256 + 32 * ks + 8 * kq);
; #pragma unroll
;                 for (int nt = 0; nt < 6; ++nt)
; #pragma unroll
;                     for (int tt = 0; tt < 3; ++tt) acc[nt][tt] = __builtin_amdgcn_mfma_f32_16x16x32_bf16(aw[nt], bq[tt], acc[nt][tt], 0, 0, 0);
;             }
	v_lshlrev_b32_e32 v253, 16, v144
	s_waitcnt lgkmcnt(0)
	v_lshlrev_b32_e32 v252, 16, v148
	v_pk_fma_f32 v[94:95], v[252:253], v[252:253], v[94:95]
	v_and_b32_e32 v253, 0xffff0000, v144
	v_and_b32_e32 v252, 0xffff0000, v148
	v_pk_fma_f32 v[94:95], v[252:253], v[252:253], v[94:95]
	v_lshlrev_b32_e32 v253, 16, v145
	v_lshlrev_b32_e32 v252, 16, v149
	v_pk_fma_f32 v[94:95], v[252:253], v[252:253], v[94:95]
	v_and_b32_e32 v253, 0xffff0000, v145
	v_and_b32_e32 v252, 0xffff0000, v149
	v_pk_fma_f32 v[94:95], v[252:253], v[252:253], v[94:95]
	v_lshlrev_b32_e32 v253, 16, v146
	v_lshlrev_b32_e32 v252, 16, v150
	v_pk_fma_f32 v[94:95], v[252:253], v[252:253], v[94:95]
	v_and_b32_e32 v253, 0xffff0000, v146
	v_and_b32_e32 v252, 0xffff0000, v150
	v_pk_fma_f32 v[94:95], v[252:253], v[252:253], v[94:95]
	v_lshlrev_b32_e32 v253, 16, v147
	v_lshlrev_b32_e32 v252, 16, v151
	v_pk_fma_f32 v[94:95], v[252:253], v[252:253], v[94:95]
	v_and_b32_e32 v253, 0xffff0000, v147
	v_and_b32_e32 v252, 0xffff0000, v151
	v_pk_fma_f32 v[94:95], v[252:253], v[252:253], v[94:95]
	global_load_dwordx4 v[152:155], v[96:97], off offset:128
	global_load_dwordx4 v[194:197], v[138:139], off offset:128
	global_load_dwordx4 v[198:201], v[156:157], off offset:128
	global_load_dwordx4 v[202:205], v[214:215], off offset:128
	global_load_dwordx4 v[206:209], v[216:217], off offset:128
	global_load_dwordx4 v[210:213], v[218:219], off offset:128
	s_waitcnt vmcnt(6)
	v_mfma_f32_16x16x32_bf16 v[86:89], v[2:5], v[90:93], v[86:89]
	v_mfma_f32_16x16x32_bf16 v[82:85], v[6:9], v[90:93], v[82:85]
	v_mfma_f32_16x16x32_bf16 v[78:81], v[10:13], v[90:93], v[78:81]
	v_mfma_f32_16x16x32_bf16 v[74:77], v[14:17], v[90:93], v[74:77]
	v_mfma_f32_16x16x32_bf16 v[70:73], v[102:105], v[90:93], v[70:73]
	v_mfma_f32_16x16x32_bf16 v[66:69], v[106:109], v[90:93], v[66:69]
	ds_read_b128 v[90:93], v220 offset:128
	v_mfma_f32_16x16x32_bf16 v[62:65], v[2:5], v[144:147], v[62:65]
	v_mfma_f32_16x16x32_bf16 v[58:61], v[6:9], v[144:147], v[58:61]
	v_mfma_f32_16x16x32_bf16 v[54:57], v[10:13], v[144:147], v[54:57]
	v_mfma_f32_16x16x32_bf16 v[46:49], v[14:17], v[144:147], v[46:49]
	v_mfma_f32_16x16x32_bf16 v[50:53], v[102:105], v[144:147], v[50:53]
	v_mfma_f32_16x16x32_bf16 v[42:45], v[106:109], v[144:147], v[42:45]
	s_waitcnt lgkmcnt(0)
	v_lshlrev_b32_e32 v144, 16, v90
	v_fmac_f32_e32 v143, v144, v144
	v_and_b32_e32 v144, 0xffff0000, v90
	v_lshlrev_b32_e32 v145, 16, v91
	v_pk_mul_f32 v[144:145], v[144:145], v[144:145]
	v_mfma_f32_16x16x32_bf16 v[38:41], v[2:5], v[148:151], v[38:41]
	v_add_f32_e32 v143, v144, v143
	v_add_f32_e32 v143, v145, v143
	v_and_b32_e32 v144, 0xffff0000, v91
	v_lshlrev_b32_e32 v145, 16, v92
	v_pk_mul_f32 v[144:145], v[144:145], v[144:145]
	v_mfma_f32_16x16x32_bf16 v[34:37], v[6:9], v[148:151], v[34:37]
	v_add_f32_e32 v143, v144, v143
	v_add_f32_e32 v143, v145, v143
	v_and_b32_e32 v144, 0xffff0000, v92
	v_lshlrev_b32_e32 v145, 16, v93
	v_pk_mul_f32 v[144:145], v[144:145], v[144:145]
	v_mfma_f32_16x16x32_bf16 v[30:33], v[10:13], v[148:151], v[30:33]
	v_add_f32_e32 v143, v144, v143
	v_add_f32_e32 v143, v145, v143
	v_and_b32_e32 v144, 0xffff0000, v93
	v_mfma_f32_16x16x32_bf16 v[22:25], v[14:17], v[148:151], v[22:25]
	v_fmac_f32_e32 v143, v144, v144
	v_mfma_f32_16x16x32_bf16 v[26:29], v[102:105], v[148:151], v[26:29]
	v_mfma_f32_16x16x32_bf16 v[18:21], v[106:109], v[148:151], v[18:21]
	ds_read_b128 v[144:147], v221 offset:128
	ds_read_b128 v[148:151], v222 offset:128
	s_waitcnt lgkmcnt(1)
	v_lshlrev_b32_e32 v253, 16, v144
	s_waitcnt lgkmcnt(0)
	v_lshlrev_b32_e32 v252, 16, v148
	v_pk_fma_f32 v[94:95], v[252:253], v[252:253], v[94:95]
	v_and_b32_e32 v253, 0xffff0000, v144
	v_and_b32_e32 v252, 0xffff0000, v148
	v_pk_fma_f32 v[94:95], v[252:253], v[252:253], v[94:95]
	v_lshlrev_b32_e32 v253, 16, v145
	v_lshlrev_b32_e32 v252, 16, v149
	v_pk_fma_f32 v[94:95], v[252:253], v[252:253], v[94:95]
	v_and_b32_e32 v253, 0xffff0000, v145
	v_and_b32_e32 v252, 0xffff0000, v149
	v_pk_fma_f32 v[94:95], v[252:253], v[252:253], v[94:95]
	v_lshlrev_b32_e32 v253, 16, v146
	v_lshlrev_b32_e32 v252, 16, v150
	v_pk_fma_f32 v[94:95], v[252:253], v[252:253], v[94:95]
	v_and_b32_e32 v253, 0xffff0000, v146
	v_and_b32_e32 v252, 0xffff0000, v150
	v_pk_fma_f32 v[94:95], v[252:253], v[252:253], v[94:95]
	v_lshlrev_b32_e32 v253, 16, v147
	v_lshlrev_b32_e32 v252, 16, v151
	v_pk_fma_f32 v[94:95], v[252:253], v[252:253], v[94:95]
	v_and_b32_e32 v253, 0xffff0000, v147
	v_and_b32_e32 v252, 0xffff0000, v151
	v_pk_fma_f32 v[94:95], v[252:253], v[252:253], v[94:95]
	global_load_dwordx4 v[2:5], v[96:97], off offset:192
	global_load_dwordx4 v[6:9], v[138:139], off offset:192
	global_load_dwordx4 v[10:13], v[156:157], off offset:192
	global_load_dwordx4 v[14:17], v[214:215], off offset:192
	global_load_dwordx4 v[102:105], v[216:217], off offset:192
	global_load_dwordx4 v[106:109], v[218:219], off offset:192
	s_waitcnt vmcnt(6)
; __device__ __forceinline__ float bf2f(bf16_t v) { return __uint_as_float(((unsigned)v) << 16); }
; #define LAS __attribute__((address_space(3)))
; __device__ __forceinline__ void ph_prep(bf16_t* Z, const bf16_t* WUQ, const bf16_t* WUKV, const bf16_t* D64, const float* qkq, const float* qkk,
;                                         bf16_t* Q, bf16_t* Kb, bf16_t* Vb, bf16_t* F1lat, bf16_t* F1ctx, unsigned char* lds_) { PH_IDS;
;     ...
; #pragma unroll 4
;             for (int ks = 0; ks < 8; ++ks) {
;                 bf16x8 bq[3], aw[6];
; #pragma unroll
;                 for (int tt = 0; tt < 3; ++tt) { bq[tt] = *(const LAS bf16x8*)(sm + O_QC + rl[tt] * P_QC + (32 * ks + 8 * kq) * 2);
; #pragma unroll
;                     for (int e = 0; e < 8; ++e) { const float f = bf2f((bf16_t)bq[tt][e]); ssq[tt] += f * f; } }
; #pragma unroll
;                 for (int nt = 0; nt < 6; ++nt) aw[nt] = *(const bf16x8*)(WUQ + (size_t)(h * 96 + 16 * nt + c16) * 256 + 32 * ks + 8 * kq);
; #pragma unroll
;                 for (int nt = 0; nt < 6; ++nt)
; #pragma unroll
;                     for (int tt = 0; tt < 3; ++tt) acc[nt][tt] = __builtin_amdgcn_mfma_f32_16x16x32_bf16(aw[nt], bq[tt], acc[nt][tt], 0, 0, 0);
;             }
	v_mfma_f32_16x16x32_bf16 v[86:89], v[152:155], v[90:93], v[86:89]
	v_mfma_f32_16x16x32_bf16 v[82:85], v[194:197], v[90:93], v[82:85]
	v_mfma_f32_16x16x32_bf16 v[78:81], v[198:201], v[90:93], v[78:81]
	v_mfma_f32_16x16x32_bf16 v[74:77], v[202:205], v[90:93], v[74:77]
	v_mfma_f32_16x16x32_bf16 v[70:73], v[206:209], v[90:93], v[70:73]
	v_mfma_f32_16x16x32_bf16 v[66:69], v[210:213], v[90:93], v[66:69]
	ds_read_b128 v[90:93], v220 offset:192
	v_mfma_f32_16x16x32_bf16 v[62:65], v[152:155], v[144:147], v[62:65]
	v_mfma_f32_16x16x32_bf16 v[58:61], v[194:197], v[144:147], v[58:61]
	v_mfma_f32_16x16x32_bf16 v[54:57], v[198:201], v[144:147], v[54:57]
	v_mfma_f32_16x16x32_bf16 v[46:49], v[202:205], v[144:147], v[46:49]
	v_mfma_f32_16x16x32_bf16 v[50:53], v[206:209], v[144:147], v[50:53]
	v_mfma_f32_16x16x32_bf16 v[42:45], v[210:213], v[144:147], v[42:45]
	s_waitcnt lgkmcnt(0)
	v_lshlrev_b32_e32 v144, 16, v90
	v_fmac_f32_e32 v143, v144, v144
	v_and_b32_e32 v144, 0xffff0000, v90
	v_lshlrev_b32_e32 v145, 16, v91
	v_pk_mul_f32 v[144:145], v[144:145], v[144:145]
	v_mfma_f32_16x16x32_bf16 v[38:41], v[152:155], v[148:151], v[38:41]
	v_add_f32_e32 v143, v144, v143
	v_add_f32_e32 v143, v145, v143
	v_and_b32_e32 v144, 0xffff0000, v91
	v_lshlrev_b32_e32 v145, 16, v92
	v_pk_mul_f32 v[144:145], v[144:145], v[144:145]
	v_mfma_f32_16x16x32_bf16 v[34:37], v[194:197], v[148:151], v[34:37]
	v_add_f32_e32 v143, v144, v143
	v_add_f32_e32 v143, v145, v143
	v_and_b32_e32 v144, 0xffff0000, v92
	v_lshlrev_b32_e32 v145, 16, v93
	v_pk_mul_f32 v[144:145], v[144:145], v[144:145]
	v_mfma_f32_16x16x32_bf16 v[30:33], v[198:201], v[148:151], v[30:33]
	v_add_f32_e32 v143, v144, v143
	v_add_f32_e32 v143, v145, v143
	v_and_b32_e32 v144, 0xffff0000, v93
	v_mfma_f32_16x16x32_bf16 v[22:25], v[202:205], v[148:151], v[22:25]
	v_fmac_f32_e32 v143, v144, v144
	v_mfma_f32_16x16x32_bf16 v[26:29], v[206:209], v[148:151], v[26:29]
	v_mfma_f32_16x16x32_bf16 v[18:21], v[210:213], v[148:151], v[18:21]
	ds_read_b128 v[144:147], v221 offset:192
	ds_read_b128 v[148:151], v222 offset:192
	s_waitcnt lgkmcnt(1)
	v_lshlrev_b32_e32 v253, 16, v144
	s_waitcnt lgkmcnt(0)
	v_lshlrev_b32_e32 v252, 16, v148
	v_pk_fma_f32 v[94:95], v[252:253], v[252:253], v[94:95]
	v_and_b32_e32 v253, 0xffff0000, v144
	v_and_b32_e32 v252, 0xffff0000, v148
	v_pk_fma_f32 v[94:95], v[252:253], v[252:253], v[94:95]
	v_lshlrev_b32_e32 v253, 16, v145
	v_lshlrev_b32_e32 v252, 16, v149
	v_pk_fma_f32 v[94:95], v[252:253], v[252:253], v[94:95]
	v_and_b32_e32 v253, 0xffff0000, v145
	v_and_b32_e32 v252, 0xffff0000, v149
	v_pk_fma_f32 v[94:95], v[252:253], v[252:253], v[94:95]
	v_lshlrev_b32_e32 v253, 16, v146
	v_lshlrev_b32_e32 v252, 16, v150
	v_pk_fma_f32 v[94:95], v[252:253], v[252:253], v[94:95]
	v_and_b32_e32 v253, 0xffff0000, v146
	v_and_b32_e32 v252, 0xffff0000, v150
	v_pk_fma_f32 v[94:95], v[252:253], v[252:253], v[94:95]
	v_lshlrev_b32_e32 v253, 16, v147
	v_lshlrev_b32_e32 v252, 16, v151
	v_pk_fma_f32 v[94:95], v[252:253], v[252:253], v[94:95]
	v_and_b32_e32 v253, 0xffff0000, v147
	v_and_b32_e32 v252, 0xffff0000, v151
	v_pk_fma_f32 v[94:95], v[252:253], v[252:253], v[94:95]
	s_cmpk_eq_i32 s12, 0x200
	s_cbranch_scc1 .Lqpf_b_L1
	global_load_dwordx4 v[152:155], v[96:97], off offset:256
	global_load_dwordx4 v[194:197], v[138:139], off offset:256
	global_load_dwordx4 v[198:201], v[156:157], off offset:256
	global_load_dwordx4 v[202:205], v[214:215], off offset:256
	global_load_dwordx4 v[206:209], v[216:217], off offset:256
	global_load_dwordx4 v[210:213], v[218:219], off offset:256
	s_waitcnt vmcnt(6)
	s_branch .Lqpf_c_L1

; #define LAS __attribute__((address_space(3)))
; __device__ __forceinline__ void ph_prep(bf16_t* Z, const bf16_t* WUQ, const bf16_t* WUKV, const bf16_t* D64, const float* qkq, const float* qkk,
;                                         bf16_t* Q, bf16_t* Kb, bf16_t* Vb, bf16_t* F1lat, bf16_t* F1ctx, unsigned char* lds_) { PH_IDS;
;     ...
; #pragma unroll 4
;             for (int ks = 0; ks < 8; ++ks) {
;                 bf16x8 bq[3], aw[6];
; #pragma unroll
;                 for (int tt = 0; tt < 3; ++tt) { bq[tt] = *(const LAS bf16x8*)(sm + O_QC + rl[tt] * P_QC + (32 * ks + 8 * kq) * 2);
; #pragma unroll
;                     for (int e = 0; e < 8; ++e) { const float f = bf2f((bf16_t)bq[tt][e]); ssq[tt] += f * f; } }
; #pragma unroll
;                 for (int nt = 0; nt < 6; ++nt) aw[nt] = *(const bf16x8*)(WUQ + (size_t)(h * 96 + 16 * nt + c16) * 256 + 32 * ks + 8 * kq);
; #pragma unroll
;                 for (int nt = 0; nt < 6; ++nt)
; #pragma unroll
;                     for (int tt = 0; tt < 3; ++tt) acc[nt][tt] = __builtin_amdgcn_mfma_f32_16x16x32_bf16(aw[nt], bq[tt], acc[nt][tt], 0, 0, 0);
;             }
; #pragma unroll
;             for (int tt = 0; tt < 3; ++tt) {
;                 float s1 = ssq[tt]; s1 += __shfl_xor(s1, 16); s1 += __shfl_xor(s1, 32);
;                 const float rstd = rsqrtf(s1 * (1.f / 256) + EPS);
;                 float ss = 0.f;
; #pragma unroll
;                 for (int nt = 0; nt < 6; ++nt)
; #pragma unroll
;                     for (int r = 0; r < 4; ++r) ss += acc[nt][tt][r] * acc[nt][tt][r];
;                 ss += __shfl_xor(ss, 16); ss += __shfl_xor(ss, 32);
;                 const float fac = rstd * rsqrtf(rstd * rstd * ss * (1.f / 96) + EPS) * 0.14724727430627066f;
;                 const int row = rowc[tt]; const bool lat = row < RL; const int b = row_batch(row), t = lat ? (row & 2047) : ((row - RL) & 255), qi = lat ? t : 2048 + t;
;                 bf16_t* qo = Q + ((size_t)(b * 4 + h) * 2304 + qi) * 96 + 4 * kq;
; #pragma unroll
;                 for (int nt = 0; nt < 6; ++nt) {
;                     const f32x4 w = *(const f32x4*)(qkq + 16 * nt + 4 * kq);
;                     float v[4];
; #pragma unroll
;                     for (int r = 0; r < 4; ++r) v[r] = acc[nt][tt][r] * fac * w[r];
;                     if (nt >= 4) rope16(v, kq, nt == 4 ? (float)(t >> 6) : (float)(t & 63), lat);
.Lqpf_c_L1:
	v_mfma_f32_16x16x32_bf16 v[86:89], v[2:5], v[90:93], v[86:89]
	v_mfma_f32_16x16x32_bf16 v[62:65], v[2:5], v[144:147], v[62:65]
	v_mfma_f32_16x16x32_bf16 v[38:41], v[2:5], v[148:151], v[38:41]
	v_mfma_f32_16x16x32_bf16 v[82:85], v[6:9], v[90:93], v[82:85]
	v_mfma_f32_16x16x32_bf16 v[58:61], v[6:9], v[144:147], v[58:61]
	v_mfma_f32_16x16x32_bf16 v[34:37], v[6:9], v[148:151], v[34:37]
	v_mfma_f32_16x16x32_bf16 v[78:81], v[10:13], v[90:93], v[78:81]
	v_mfma_f32_16x16x32_bf16 v[54:57], v[10:13], v[144:147], v[54:57]
	v_mfma_f32_16x16x32_bf16 v[30:33], v[10:13], v[148:151], v[30:33]
	v_mfma_f32_16x16x32_bf16 v[74:77], v[14:17], v[90:93], v[74:77]
	v_mfma_f32_16x16x32_bf16 v[46:49], v[14:17], v[144:147], v[46:49]
	v_mfma_f32_16x16x32_bf16 v[22:25], v[14:17], v[148:151], v[22:25]
	v_mfma_f32_16x16x32_bf16 v[70:73], v[102:105], v[90:93], v[70:73]
	v_mfma_f32_16x16x32_bf16 v[50:53], v[102:105], v[144:147], v[50:53]
	v_mfma_f32_16x16x32_bf16 v[26:29], v[102:105], v[148:151], v[26:29]
	v_mfma_f32_16x16x32_bf16 v[66:69], v[106:109], v[90:93], v[66:69]
	v_mfma_f32_16x16x32_bf16 v[42:45], v[106:109], v[144:147], v[42:45]
	v_mfma_f32_16x16x32_bf16 v[18:21], v[106:109], v[148:151], v[18:21]
	s_cbranch_scc0 .LBB0_2409
	v_mov_b64_e32 v[144:145], v[224:225]
	v_mov_b64_e32 v[146:147], v[226:227]
	v_mul_f32_e32 v150, v87, v87
	v_fmac_f32_e32 v150, v86, v86
	v_fmac_f32_e32 v150, v88, v88
	v_fmac_f32_e32 v150, v89, v89
	v_fmac_f32_e32 v150, v82, v82
	v_fmac_f32_e32 v150, v83, v83
	v_fmac_f32_e32 v150, v84, v84
	v_fmac_f32_e32 v150, v85, v85
	v_fmac_f32_e32 v150, v78, v78
	v_and_b32_e32 v91, 64, v1
	v_fmac_f32_e32 v150, v79, v79
	v_xor_b32_e32 v90, 16, v1
	v_add_u32_e32 v91, 64, v91
	v_fmac_f32_e32 v150, v80, v80
	v_cmp_lt_i32_e64 s[12:13], v90, v91
	v_fmac_f32_e32 v150, v81, v81
	v_xor_b32_e32 v100, 32, v1
	v_cndmask_b32_e64 v90, v1, v90, s[12:13]
	v_fmac_f32_e32 v150, v74, v74
	v_cmp_lt_i32_e64 s[12:13], v100, v91
	v_lshlrev_b32_e32 v91, 2, v90
	v_fmac_f32_e32 v150, v75, v75
	ds_bpermute_b32 v153, v91, v143
	v_fmac_f32_e32 v150, v76, v76
	v_pk_mul_f32 v[96:97], v[70:71], v[70:71]
	v_fmac_f32_e32 v150, v77, v77
	v_add_f32_e32 v96, v96, v150
	v_pk_mul_f32 v[92:93], v[72:73], v[72:73]
	v_add_f32_e32 v96, v97, v96
	v_cndmask_b32_e64 v100, v1, v100, s[12:13]
	v_add_f32_e32 v92, v92, v96
	v_pk_mul_f32 v[148:149], v[66:67], v[66:67]
	v_lshlrev_b32_e32 v90, 2, v100
	s_waitcnt lgkmcnt(0)
	v_add_f32_e32 v143, v143, v153
	v_add_f32_e32 v92, v93, v92
	ds_bpermute_b32 v153, v90, v143
	v_add_f32_e32 v92, v148, v92
	v_pk_mul_f32 v[138:139], v[68:69], v[68:69]
	v_add_f32_e32 v92, v149, v92
	v_add_f32_e32 v92, v138, v92
	v_add_f32_e32 v92, v139, v92
	ds_bpermute_b32 v93, v91, v92
	s_waitcnt lgkmcnt(1)
	v_add_f32_e32 v143, v143, v153
	v_fmamk_f32 v143, v143, 0x3b800000, v175
	v_mul_f32_e32 v96, 0x4b800000, v143
	v_cmp_gt_f32_e64 s[12:13], s53, v143
	v_cmp_gt_i32_e32 vcc, s50, v191
	s_waitcnt lgkmcnt(0)
	v_add_f32_e32 v97, v92, v93
	v_cndmask_b32_e64 v96, v143, v96, s[12:13]
	v_cndmask_b32_e32 v152, v177, v178, vcc
	v_rsq_f32_e32 v96, v96
	v_and_b32_e32 v152, v152, v191
	ds_bpermute_b32 v138, v90, v97
	v_cndmask_b32_e32 v151, v193, v192, vcc
	v_or_b32_e32 v100, 0x800, v152
	v_lshl_add_u32 v151, v151, 2, s29
	v_cndmask_b32_e32 v100, v100, v152, vcc
	v_mad_i64_i32 v[92:93], s[14:15], v151, s51, v[100:101]
	v_mul_f32_e32 v100, 0x45800000, v96
	v_cndmask_b32_e64 v100, v96, v100, s[12:13]
	v_mul_f32_e32 v96, v100, v100
	s_waitcnt lgkmcnt(0)
	v_add_f32_e32 v97, v97, v138
	v_mul_f32_e32 v96, v97, v96
	v_fmamk_f32 v96, v96, 0x3c2aaaab, v175
	v_mul_f32_e32 v97, 0x4b800000, v96
	v_cmp_gt_f32_e64 s[12:13], s53, v96
	s_nop 1
	v_cndmask_b32_e64 v96, v96, v97, s[12:13]
	v_rsq_f32_e32 v138, v96
	v_mad_u64_u32 v[96:97], s[14:15], v92, s52, v[110:111]
	v_mad_i32_i24 v97, v93, s52, v97
	v_mul_f32_e32 v92, 0x45800000, v138
	v_cndmask_b32_e64 v92, v138, v92, s[12:13]
	v_mul_f32_e32 v92, v100, v92
	v_mul_f32_e32 v92, 0x3e16c7fd, v92
	v_mul_f32_e32 v86, v86, v92
	v_mul_f32_e32 v87, v87, v92
	v_mul_f32_e32 v86, v144, v86
	v_mul_f32_e32 v87, v145, v87
	v_mul_f32_e32 v88, v88, v92
	v_mul_f32_e32 v89, v89, v92
	v_mul_f32_e32 v88, v146, v88
	v_mul_f32_e32 v89, v147, v89
	v_cvt_pk_bf16_f32 v86, v86, v87
	v_cvt_pk_bf16_f32 v87, v88, v89
	global_store_dwordx2 v[96:97], v[86:87], off
	v_mov_b64_e32 v[86:87], v[228:229]
	v_mov_b64_e32 v[88:89], v[230:231]
	v_mul_f32_e32 v82, v82, v92
	v_mul_f32_e32 v83, v83, v92
	v_mul_f32_e32 v84, v84, v92
	v_mul_f32_e32 v85, v85, v92
	v_mul_f32_e32 v78, v78, v92
	v_mul_f32_e32 v79, v79, v92
	v_mul_f32_e32 v80, v80, v92
	v_mul_f32_e32 v81, v81, v92
	v_mul_f32_e32 v74, v74, v92
	v_mul_f32_e32 v75, v75, v92
	v_mul_f32_e32 v76, v76, v92
	v_mul_f32_e32 v77, v77, v92
	v_mul_f32_e32 v70, v70, v92
	v_mul_f32_e32 v71, v71, v92
	v_mul_f32_e32 v72, v72, v92
	v_mul_f32_e32 v73, v73, v92
	v_mul_f32_e32 v66, v66, v92
	v_mul_f32_e32 v67, v67, v92
	v_mul_f32_e32 v68, v68, v92
	v_mul_f32_e32 v69, v69, v92
	v_mul_f32_e32 v82, v86, v82
	v_mul_f32_e32 v83, v87, v83
	v_mul_f32_e32 v84, v88, v84
	v_mul_f32_e32 v85, v89, v85
	v_cvt_pk_bf16_f32 v82, v82, v83
	v_cvt_pk_bf16_f32 v83, v84, v85
	global_store_dwordx2 v[96:97], v[82:83], off offset:32
	v_mov_b64_e32 v[82:83], v[232:233]
	v_mov_b64_e32 v[84:85], v[234:235]
	v_mul_f32_e32 v78, v82, v78
	v_mul_f32_e32 v79, v83, v79
	v_mul_f32_e32 v80, v84, v80
	v_mul_f32_e32 v81, v85, v81
	v_cvt_pk_bf16_f32 v78, v78, v79
	v_cvt_pk_bf16_f32 v79, v80, v81
	global_store_dwordx2 v[96:97], v[78:79], off offset:64
	v_mov_b64_e32 v[78:79], v[236:237]
	v_mov_b64_e32 v[80:81], v[238:239]
	v_mul_f32_e32 v74, v78, v74
	v_mul_f32_e32 v75, v79, v75
	v_mul_f32_e32 v76, v80, v76
	v_mul_f32_e32 v77, v81, v77
	v_cvt_pk_bf16_f32 v74, v74, v75
	v_cvt_pk_bf16_f32 v75, v76, v77
	global_store_dwordx2 v[96:97], v[74:75], off offset:96
	v_mov_b64_e32 v[74:75], v[240:241]
	v_mov_b64_e32 v[76:77], v[242:243]
	v_lshrrev_b32_e32 v78, 6, v152
	v_cvt_f32_ubyte0_e32 v78, v78
	v_mul_f32_e32 v79, v167, v78
	v_mul_f32_e32 v80, v166, v78
	v_mul_f32_e32 v81, v165, v78
	v_mul_f32_e32 v78, v164, v78
	v_mul_f32_e32 v81, 0.15915494, v81
	v_mul_f32_e32 v78, 0.15915494, v78
	v_mul_f32_e32 v79, 0.15915494, v79
	v_mul_f32_e32 v80, 0.15915494, v80
	v_cos_f32_e32 v84, v81
	v_sin_f32_e32 v81, v81
	v_cos_f32_e32 v85, v78
	v_sin_f32_e32 v78, v78
	v_cos_f32_e32 v82, v79
	v_sin_f32_e32 v79, v79
	v_cos_f32_e32 v83, v80
	v_sin_f32_e32 v80, v80
	v_mul_f32_e32 v70, v74, v70
	v_mul_f32_e32 v71, v75, v71
	v_mul_f32_e32 v72, v76, v72
	v_mul_f32_e32 v73, v77, v73
	ds_bpermute_b32 v76, v90, v71
	ds_bpermute_b32 v77, v90, v70
	ds_bpermute_b32 v74, v90, v73
	ds_bpermute_b32 v75, v90, v72
	s_waitcnt lgkmcnt(3)
; __device__ __forceinline__ unsigned pk2(float lo, float hi) { unsigned r; asm volatile("v_cvt_pk_bf16_f32 %0, %1, %2" : "=v"(r) : "v"(lo), "v"(hi)); return r; }
; __device__ __forceinline__ void rope16(float (&v)[4], int kq, float pos, bool on) {
; #pragma unroll
;     for (int r = 0; r < 4; ++r) {
;         const int j = (4 * kq + r) & 7;
;         const float ang = pos * exp2f(-(float)j * (13.287712379549449f / 8.f)), cs = __cosf(ang), sn = __sinf(ang);
;         const float other = __shfl_xor(v[r], 32);
;         const float rot = kq < 2 ? v[r] * cs - other * sn : other * sn + v[r] * cs;
;         v[r] = on ? rot : v[r];
;     }
; __device__ __forceinline__ void ph_prep(bf16_t* Z, const bf16_t* WUQ, const bf16_t* WUKV, const bf16_t* D64, const float* qkq, const float* qkk,
;                                         bf16_t* Q, bf16_t* Kb, bf16_t* Vb, bf16_t* F1lat, bf16_t* F1ctx, unsigned char* lds_) { PH_IDS;
;     ...
;             for (int tt = 0; tt < 3; ++tt) {
;                 float s1 = ssq[tt]; s1 += __shfl_xor(s1, 16); s1 += __shfl_xor(s1, 32);
;                 const float rstd = rsqrtf(s1 * (1.f / 256) + EPS);
;                 float ss = 0.f;
; #pragma unroll
;                 for (int nt = 0; nt < 6; ++nt)
; #pragma unroll
;                     for (int r = 0; r < 4; ++r) ss += acc[nt][tt][r] * acc[nt][tt][r];
;                 ss += __shfl_xor(ss, 16); ss += __shfl_xor(ss, 32);
;                 const float fac = rstd * rsqrtf(rstd * rstd * ss * (1.f / 96) + EPS) * 0.14724727430627066f;
;                 const int row = rowc[tt]; const bool lat = row < RL; const int b = row_batch(row), t = lat ? (row & 2047) : ((row - RL) & 255), qi = lat ? t : 2048 + t;
;                 bf16_t* qo = Q + ((size_t)(b * 4 + h) * 2304 + qi) * 96 + 4 * kq;
; #pragma unroll
;                 for (int nt = 0; nt < 6; ++nt) {
;                     const f32x4 w = *(const f32x4*)(qkq + 16 * nt + 4 * kq);
;                     float v[4];
; #pragma unroll
;                     for (int r = 0; r < 4; ++r) v[r] = acc[nt][tt][r] * fac * w[r];
;                     if (nt >= 4) rope16(v, kq, nt == 4 ? (float)(t >> 6) : (float)(t & 63), lat);
;                     fa::u32x2 o; o.x = fa::pk2(v[0], v[1]); o.y = fa::pk2(v[2], v[3]);
;                     if (valid[tt]) *(fa::u32x2*)(qo + 16 * nt) = o;
	v_mul_f32_e32 v76, v81, v76
	s_waitcnt lgkmcnt(2)
	v_mul_f32_e32 v77, v78, v77
	s_waitcnt lgkmcnt(1)
	v_mul_f32_e32 v74, v79, v74
	s_waitcnt lgkmcnt(0)
	v_mul_f32_e32 v75, v80, v75
	v_cndmask_b32_e64 v76, v76, -v76, s[4:5]
	v_cndmask_b32_e64 v77, v77, -v77, s[4:5]
	v_cndmask_b32_e64 v74, v74, -v74, s[4:5]
	v_cndmask_b32_e64 v75, v75, -v75, s[4:5]
	v_fmac_f32_e32 v76, v84, v71
	v_fmac_f32_e32 v77, v85, v70
	v_fmac_f32_e32 v74, v82, v73
	v_fmac_f32_e32 v75, v83, v72
	v_cndmask_b32_e32 v71, v71, v76, vcc
	v_cndmask_b32_e32 v70, v70, v77, vcc
	v_cndmask_b32_e32 v73, v73, v74, vcc
	v_cndmask_b32_e32 v72, v72, v75, vcc
	v_cvt_pk_bf16_f32 v70, v70, v71
	v_cvt_pk_bf16_f32 v71, v72, v73
	global_store_dwordx2 v[96:97], v[70:71], off offset:128
	v_mov_b64_e32 v[70:71], v[244:245]
	v_mov_b64_e32 v[72:73], v[246:247]
	v_mul_f32_e32 v76, v165, v190
	v_mul_f32_e32 v77, v164, v190
	v_mul_f32_e32 v74, v167, v190
	v_mul_f32_e32 v75, v166, v190
	v_mul_f32_e32 v76, 0.15915494, v76
	v_mul_f32_e32 v77, 0.15915494, v77
	v_mul_f32_e32 v74, 0.15915494, v74
	v_mul_f32_e32 v75, 0.15915494, v75
	v_cos_f32_e32 v80, v76
	v_sin_f32_e32 v76, v76
	v_cos_f32_e32 v81, v77
	v_sin_f32_e32 v77, v77
	v_cos_f32_e32 v78, v74
	v_sin_f32_e32 v74, v74
	v_cos_f32_e32 v79, v75
	v_sin_f32_e32 v75, v75
	ds_bpermute_b32 v82, v91, v95
	v_mul_f32_e32 v66, v66, v70
	v_mul_f32_e32 v67, v67, v71
	v_mul_f32_e32 v68, v68, v72
	v_mul_f32_e32 v69, v69, v73
	ds_bpermute_b32 v72, v90, v67
	ds_bpermute_b32 v73, v90, v66
	ds_bpermute_b32 v70, v90, v69
	ds_bpermute_b32 v71, v90, v68
	s_waitcnt lgkmcnt(3)
	v_mul_f32_e32 v72, v76, v72
	s_waitcnt lgkmcnt(2)
	v_mul_f32_e32 v73, v77, v73
	s_waitcnt lgkmcnt(1)
	v_mul_f32_e32 v70, v74, v70
	s_waitcnt lgkmcnt(0)
	v_mul_f32_e32 v71, v75, v71
	v_cndmask_b32_e64 v72, v72, -v72, s[4:5]
	v_cndmask_b32_e64 v73, v73, -v73, s[4:5]
	v_cndmask_b32_e64 v70, v70, -v70, s[4:5]
	v_cndmask_b32_e64 v71, v71, -v71, s[4:5]
	v_fmac_f32_e32 v72, v80, v67
	v_fmac_f32_e32 v73, v81, v66
	v_fmac_f32_e32 v70, v78, v69
	v_fmac_f32_e32 v71, v79, v68
	v_cndmask_b32_e32 v67, v67, v72, vcc
	v_cndmask_b32_e32 v66, v66, v73, vcc
	v_cndmask_b32_e32 v69, v69, v70, vcc
	v_cndmask_b32_e32 v68, v68, v71, vcc
	v_cvt_pk_bf16_f32 v66, v66, v67
	v_cvt_pk_bf16_f32 v67, v68, v69
	global_store_dwordx2 v[96:97], v[66:67], off offset:160
	v_mov_b64_e32 v[70:71], v[224:225]
	v_mov_b64_e32 v[72:73], v[226:227]
	v_mul_f32_e32 v68, v63, v63
	v_fmac_f32_e32 v68, v62, v62
	v_fmac_f32_e32 v68, v64, v64
	v_fmac_f32_e32 v68, v65, v65
	v_fmac_f32_e32 v68, v58, v58
	v_fmac_f32_e32 v68, v59, v59
	v_fmac_f32_e32 v68, v60, v60
	v_fmac_f32_e32 v68, v61, v61
	v_fmac_f32_e32 v68, v54, v54
	v_fmac_f32_e32 v68, v55, v55
	v_fmac_f32_e32 v68, v56, v56
	v_fmac_f32_e32 v68, v57, v57
	v_fmac_f32_e32 v68, v46, v46
	v_fmac_f32_e32 v68, v47, v47
	v_fmac_f32_e32 v68, v48, v48
	v_pk_mul_f32 v[74:75], v[50:51], v[50:51]
	v_cmp_gt_i32_e32 vcc, s50, v187
	v_fmac_f32_e32 v68, v49, v49
	v_add_f32_e32 v68, v74, v68
	v_cndmask_b32_e32 v69, v189, v188, vcc
	v_cndmask_b32_e32 v80, v177, v178, vcc
	v_pk_mul_f32 v[66:67], v[52:53], v[52:53]
	v_lshl_add_u32 v81, v69, 2, s29
	v_and_b32_e32 v69, v80, v187
	v_add_f32_e32 v68, v75, v68
	v_or_b32_e32 v80, 0x800, v69
	v_add_f32_e32 v66, v66, v68
	v_pk_mul_f32 v[78:79], v[42:43], v[42:43]
	v_cndmask_b32_e32 v100, v80, v69, vcc
	v_add_f32_e32 v80, v95, v82
	v_add_f32_e32 v66, v67, v66
	ds_bpermute_b32 v82, v90, v80
	v_add_f32_e32 v66, v78, v66
	v_pk_mul_f32 v[76:77], v[44:45], v[44:45]
	v_add_f32_e32 v66, v79, v66
	v_add_f32_e32 v66, v76, v66
	v_add_f32_e32 v66, v77, v66
	ds_bpermute_b32 v67, v91, v66
	s_waitcnt lgkmcnt(1)
	v_add_f32_e32 v80, v80, v82
	v_fmamk_f32 v80, v80, 0x3b800000, v175
	v_mul_f32_e32 v68, 0x4b800000, v80
	v_cmp_gt_f32_e64 s[12:13], s53, v80
	s_waitcnt lgkmcnt(0)
	v_add_f32_e32 v66, v66, v67
	ds_bpermute_b32 v67, v90, v66
	v_cndmask_b32_e64 v68, v80, v68, s[12:13]
	v_rsq_f32_e32 v68, v68
	v_mad_i64_i32 v[74:75], s[14:15], v81, s51, v[100:101]
	s_waitcnt lgkmcnt(0)
	v_add_f32_e32 v66, v66, v67
	v_mul_f32_e32 v76, 0x45800000, v68
	v_cndmask_b32_e64 v68, v68, v76, s[12:13]
	v_mul_f32_e32 v76, v68, v68
	v_mul_f32_e32 v66, v66, v76
	v_fmamk_f32 v66, v66, 0x3c2aaaab, v175
	v_mul_f32_e32 v67, 0x4b800000, v66
	v_cmp_gt_f32_e64 s[12:13], s53, v66
	s_nop 1
	v_cndmask_b32_e64 v66, v66, v67, s[12:13]
	v_rsq_f32_e32 v76, v66
	v_mad_u64_u32 v[66:67], s[14:15], v74, s52, v[110:111]
	v_mad_i32_i24 v67, v75, s52, v67
	v_mul_f32_e32 v74, 0x45800000, v76
	v_cndmask_b32_e64 v74, v76, v74, s[12:13]
	v_mul_f32_e32 v68, v68, v74
	v_mul_f32_e32 v68, 0x3e16c7fd, v68
	v_mul_f32_e32 v62, v62, v68
	v_mul_f32_e32 v63, v63, v68
	v_mul_f32_e32 v64, v64, v68
	v_mul_f32_e32 v65, v65, v68
	v_mul_f32_e32 v62, v70, v62
	v_mul_f32_e32 v63, v71, v63
	v_mul_f32_e32 v64, v72, v64
	v_mul_f32_e32 v65, v73, v65
	v_cvt_pk_bf16_f32 v62, v62, v63
	v_cvt_pk_bf16_f32 v63, v64, v65
	s_and_saveexec_b64 s[12:13], s[10:11]
	s_cbranch_execz .LBB0_2412
	global_store_dwordx2 v[66:67], v[62:63], off
